# QKV/BIN/BGRP GEMM instance: peeled first/last iterations, C=0 first touch, rstd register cache, first half of the bf16 epilogue interleaved into the last MFMA block
# speedup vs baseline: 1.0147x; 1.0006x over previous
; #define PG8_STAGE(bufoff, gbase, voff) do { _Pragma("unroll") for (int _i = 0; _i < 2; ++_i) \
;         __builtin_amdgcn_global_load_lds((const unsigned*)((const char*)(gbase) + (voff)[_i]), (LAS unsigned*)(lds + (bufoff) + ldsw + _i * 8192), 16, 0, 0); } while (0)
; #define PG8_WAIT_V(n) asm volatile("s_waitcnt vmcnt(" #n ")" ::: "memory")
; #define PG8_BAR __builtin_amdgcn_s_barrier()
; template <class Epi, bool ALIGN_EPI>
; __device__ __forceinline__ void gemm_phase(LAS unsigned char* lds, const Gemm g, const StaticOrder& S, const Epi& E, const int tid) {
;     ...
;     PG8_STAGE(PG8_SB(0, 0), cB, voffB); PG8_STAGE(PG8_SB(0, 1), cB + hB, voffB); PG8_STAGE(PG8_SA(0, 0), cA, voffA); PG8_STAGE(PG8_SA(0, 1), cA + hA, voffA);
;     if (wr == 1) PG8_BAR;
;     PG8_WAIT_V(2); PG8_BAR;
;     PG8_STAGE(PG8_SB(1, 0), cB + kstep, voffB); PG8_STAGE(PG8_SA(1, 0), cA + kstep, voffA); PG8_STAGE(PG8_SB(1, 1), cB + hB + kstep, voffB);
;     PG8_WAIT_V(6); PG8_BAR;
.LBB0_343:
	v_lshl_add_u64 v[8:9], v[144:145], 0, v[168:169]
	v_mov_b32_e32 v129, v169
	v_lshl_add_u64 v[10:11], v[144:145], 0, v[128:129]
	v_mov_b32_e32 v133, v169
	s_add_i32 m0, s25, 0x18000
	v_lshl_add_u64 v[8:9], v[8:9], 0, s[92:93]
	v_lshl_add_u64 v[14:15], v[142:143], 0, v[132:133]
	v_mov_b32_e32 v131, v169
	s_waitcnt vmcnt(2)
	s_barrier
	global_load_lds_dwordx4 v[8:9], off
	v_lshl_add_u64 v[8:9], v[10:11], 0, s[92:93]
	s_add_i32 m0, s25, 0x1a000
	s_add_i32 s53, s25, 0x8000
	v_lshl_add_u64 v[16:17], v[142:143], 0, v[130:131]
	global_load_lds_dwordx4 v[8:9], off
	v_lshl_add_u64 v[8:9], v[14:15], 0, s[92:93]
	s_mov_b32 m0, s53
	s_add_i32 s54, s25, 0xa000
	v_lshl_add_u64 v[12:13], v[0:1], 0, v[168:169]
	global_load_lds_dwordx4 v[8:9], off
	v_lshl_add_u64 v[8:9], v[16:17], 0, s[92:93]
	s_mov_b32 m0, s54
	v_lshl_add_u64 v[0:1], v[0:1], 0, v[128:129]
	global_load_lds_dwordx4 v[8:9], off
	s_add_i32 m0, s25, 0x1c000
	v_lshl_add_u64 v[8:9], v[12:13], 0, s[92:93]
	global_load_lds_dwordx4 v[8:9], off
	v_lshl_add_u64 v[0:1], v[0:1], 0, s[92:93]
	s_add_i32 m0, s25, 0x1e000
	v_and_b32_e32 v18, 15, v170
	global_load_lds_dwordx4 v[0:1], off
	v_add_u32_e32 v0, v7, v5
	s_lshr_b32 s1, s1, 6
	v_and_b32_e32 v19, 48, v170
	v_lshlrev_b32_e32 v18, 6, v18
	v_lshlrev_b32_e32 v21, 2, v170
	s_lshl_b32 s9, s9, 12
	v_add_lshl_u32 v0, v0, v6, 1
	v_mov_b32_e32 v1, v169
	v_or_b32_e32 v20, v18, v19
	s_lshl_b32 s10, s10, 13
	v_and_b32_e32 v21, 32, v21
	s_and_b32 s9, s9, 0x3000
	s_waitcnt vmcnt(6)
	s_add_i32 s55, s1, -2
	v_lshl_add_u64 v[134:135], s[94:95], 0, v[0:1]
	v_add_u32_e32 v0, v4, v2
	v_bitop3_b32 v18, v18, v21, v19 bitop3:0x36
	v_bitop3_b32 v19, s10, v20, v21 bitop3:0xf6
	s_cmpk_lt_u32 s8, 0x100
	v_add_lshl_u32 v0, v0, v3, 1
	v_or_b32_e32 v149, s9, v18
	s_cselect_b64 s[42:43], -1, 0
	s_ashr_i32 s56, s6, 31
	s_mov_b32 s39, s95
	v_lshl_add_u64 v[136:137], s[94:95], 0, v[0:1]
	s_mov_b32 s57, 0
	v_add_u32_e32 v151, 0, v19
	s_barrier
	v_mov_b32_e32 v254, -1
	s_mov_b32 s101, 0
	s_branch .LBB0_346

; #define PG8_STAGE(bufoff, gbase, voff) do { _Pragma("unroll") for (int _i = 0; _i < 2; ++_i) \
;         __builtin_amdgcn_global_load_lds((const unsigned*)((const char*)(gbase) + (voff)[_i]), (LAS unsigned*)(lds + (bufoff) + ldsw + _i * 8192), 16, 0, 0); } while (0)
; #define PG8_LDA(dst, b, h) do { _Pragma("unroll") for (int m = 0; m < 4; ++m) _Pragma("unroll") for (int k = 0; k < 2; ++k) dst[m][k] = *(const LAS bf16x8*)(lds + PG8_SA(b, h) + aoff + m * 2048 + k * 1024); } while (0)
; #define PG8_LDB(dst, b, h) do { _Pragma("unroll") for (int n = 0; n < 2; ++n) _Pragma("unroll") for (int k = 0; k < 2; ++k) dst[n][k] = *(const LAS bf16x8*)(lds + PG8_SB(b, h) + boff + n * 2048 + k * 1024); } while (0)
; #define PG8_SCHED __builtin_amdgcn_sched_barrier(0)
; __device__ __forceinline__ void load_rstd(float (&rsv)[2][4], const ssq_t* ssq, int row0) {
;     ssq_t t[2][4];
; #pragma unroll
;     for (int ai = 0; ai < 2; ++ai)
; #pragma unroll
;         for (int m = 0; m < 4; ++m) t[ai][m] = ssq[row0 + ai * HALF + m * 16];
; #pragma unroll
;     for (int ai = 0; ai < 2; ++ai)
; #pragma unroll
;         for (int m = 0; m < 4; ++m) rsv[ai][m] = __builtin_amdgcn_rsqf((float)t[ai][m] * (SSQ_INV / 1024.0f) + 1e-6f);
; }
; template <class Epi, bool ALIGN_EPI>
; __device__ __forceinline__ void gemm_phase(LAS unsigned char* lds, const Gemm g, const StaticOrder& S, const Epi& E, const int tid) {
;     ...
;             PG8_LDB(B0, 0, 0); PG8_LDB(B1, 0, 1); PG8_SCHED; PG8_LDA(At, 0, 0); PG8_STAGE(PG8_SA(1, 1), a1 + hA, voffA);
.LBB0_352:
	s_andn2_b64 vcc, exec, s[36:37]
	s_cbranch_vccnz .LBB0_355
	v_lshl_add_u64 v[142:143], v[142:143], 0, s[92:93]
	v_lshl_add_u64 v[144:145], v[144:145], 0, s[80:81]
	s_mov_b32 s10, 0
	v_readfirstlane_b32 s98, v254
	s_cmp_eq_u32 s98, s61
	s_cbranch_scc1 .Lq5_rs_ok
	v_lshrrev_b32_e32 v194, 8, v170
	v_and_b32_e32 v195, 15, v170
	v_lshl_add_u32 v194, v194, 6, v195
	s_lshl_b32 s98, s61, 8
	v_add_u32_e32 v194, s98, v194
	v_lshlrev_b32_e32 v192, 3, v194
	v_mov_b32_e32 v193, 0
	v_lshl_add_u64 v[192:193], v[192:193], 0, s[26:27]
	global_load_dwordx2 v[176:177], v[192:193], off
	global_load_dwordx2 v[178:179], v[192:193], off offset:128
	global_load_dwordx2 v[180:181], v[192:193], off offset:256
	global_load_dwordx2 v[182:183], v[192:193], off offset:384
	global_load_dwordx2 v[184:185], v[192:193], off offset:1024
	global_load_dwordx2 v[186:187], v[192:193], off offset:1152
	global_load_dwordx2 v[188:189], v[192:193], off offset:1280
	global_load_dwordx2 v[190:191], v[192:193], off offset:1408
	s_waitcnt vmcnt(0)
	v_ffbh_u32_e32 v194, v177
	v_min_u32_e32 v194, 32, v194
	v_lshlrev_b64 v[176:177], v194, v[176:177]
	v_min_u32_e32 v176, 1, v176
	v_or_b32_e32 v176, v177, v176
	v_cvt_f32_u32_e32 v176, v176
	v_sub_u32_e32 v194, 32, v194
	v_ldexp_f32 v176, v176, v194
	v_fmamk_f32 v176, v176, 0x30800000, v223
	v_rsq_f32_e32 v176, v176
	v_ffbh_u32_e32 v194, v179
	v_min_u32_e32 v194, 32, v194
	v_lshlrev_b64 v[178:179], v194, v[178:179]
	v_min_u32_e32 v178, 1, v178
	v_or_b32_e32 v178, v179, v178
	v_cvt_f32_u32_e32 v178, v178
	v_sub_u32_e32 v194, 32, v194
	v_ldexp_f32 v178, v178, v194
	v_fmamk_f32 v178, v178, 0x30800000, v223
	v_rsq_f32_e32 v178, v178
	v_ffbh_u32_e32 v194, v181
	v_min_u32_e32 v194, 32, v194
	v_lshlrev_b64 v[180:181], v194, v[180:181]
	v_min_u32_e32 v180, 1, v180
	v_or_b32_e32 v180, v181, v180
	v_cvt_f32_u32_e32 v180, v180
	v_sub_u32_e32 v194, 32, v194
	v_ldexp_f32 v180, v180, v194
	v_fmamk_f32 v180, v180, 0x30800000, v223
	v_rsq_f32_e32 v180, v180
	v_ffbh_u32_e32 v194, v183
	v_min_u32_e32 v194, 32, v194
	v_lshlrev_b64 v[182:183], v194, v[182:183]
	v_min_u32_e32 v182, 1, v182
	v_or_b32_e32 v182, v183, v182
	v_cvt_f32_u32_e32 v182, v182
	v_sub_u32_e32 v194, 32, v194
	v_ldexp_f32 v182, v182, v194
	v_fmamk_f32 v182, v182, 0x30800000, v223
	v_rsq_f32_e32 v182, v182
	v_ffbh_u32_e32 v194, v185
	v_min_u32_e32 v194, 32, v194
	v_lshlrev_b64 v[184:185], v194, v[184:185]
	v_min_u32_e32 v184, 1, v184
	v_or_b32_e32 v184, v185, v184
	v_cvt_f32_u32_e32 v184, v184
	v_sub_u32_e32 v194, 32, v194
	v_ldexp_f32 v184, v184, v194
	v_fmamk_f32 v184, v184, 0x30800000, v223
	v_rsq_f32_e32 v184, v184
	v_ffbh_u32_e32 v194, v187
	v_min_u32_e32 v194, 32, v194
	v_lshlrev_b64 v[186:187], v194, v[186:187]
	v_min_u32_e32 v186, 1, v186
	v_or_b32_e32 v186, v187, v186
	v_cvt_f32_u32_e32 v186, v186
	v_sub_u32_e32 v194, 32, v194
	v_ldexp_f32 v186, v186, v194
	v_fmamk_f32 v186, v186, 0x30800000, v223
	v_rsq_f32_e32 v186, v186
	v_ffbh_u32_e32 v194, v189
	v_min_u32_e32 v194, 32, v194
	v_lshlrev_b64 v[188:189], v194, v[188:189]
	v_min_u32_e32 v188, 1, v188
	v_or_b32_e32 v188, v189, v188
	v_cvt_f32_u32_e32 v188, v188
	v_sub_u32_e32 v194, 32, v194
	v_ldexp_f32 v188, v188, v194
	v_fmamk_f32 v188, v188, 0x30800000, v223
	v_rsq_f32_e32 v188, v188
	v_ffbh_u32_e32 v194, v191
	v_min_u32_e32 v194, 32, v194
	v_lshlrev_b64 v[190:191], v194, v[190:191]
	v_min_u32_e32 v190, 1, v190
	v_or_b32_e32 v190, v191, v190
	v_cvt_f32_u32_e32 v190, v190
	v_sub_u32_e32 v194, 32, v194
	v_ldexp_f32 v190, v190, v194
	v_fmamk_f32 v190, v190, 0x30800000, v223
	v_rsq_f32_e32 v190, v190
	v_mov_b32_e32 v172, v176
	v_mov_b32_e32 v173, v178
	v_mov_b32_e32 v236, v180
	v_mov_b32_e32 v237, v182
	v_mov_b32_e32 v238, v184
	v_mov_b32_e32 v239, v186
	v_mov_b32_e32 v230, v188
	v_mov_b32_e32 v231, v190
	v_mov_b32_e32 v254, s61
.Lq5_rs_ok:
.Lq5_first:
	s_add_i32 s11, s10, 2
	s_cmp_eq_u32 s55, s10
	s_cselect_b64 vcc, -1, 0
	v_add_u32_e32 v148, s33, v149
	s_add_i32 s10, 0, 0x14000
	ds_read_b128 v[152:155], v148
	ds_read_b128 v[156:159], v148 offset:1024
	ds_read_b128 v[160:163], v148 offset:2048
	ds_read_b128 v[164:167], v148 offset:3072
	v_add_u32_e32 v148, s10, v149
	ds_read_b128 v[176:179], v148
	ds_read_b128 v[180:183], v148 offset:1024
	ds_read_b128 v[184:187], v148 offset:2048
	ds_read_b128 v[188:191], v148 offset:3072
	v_lshl_add_u64 v[146:147], v[142:143], 0, s[92:93]
	v_cndmask_b32_e32 v147, v147, v139, vcc
	v_cndmask_b32_e32 v146, v146, v138, vcc
	v_cndmask_b32_e32 v221, v145, v141, vcc
	v_cndmask_b32_e32 v220, v144, v140, vcc
	v_lshl_add_u64 v[244:245], v[142:143], 0, v[134:135]
	s_add_i32 m0, s25, 0xc000
	ds_read_b128 v[192:195], v151
	ds_read_b128 v[196:199], v151 offset:1024
	ds_read_b128 v[200:203], v151 offset:2048
	ds_read_b128 v[204:207], v151 offset:3072
	ds_read_b128 v[208:211], v151 offset:4096
	ds_read_b128 v[212:215], v151 offset:5120
	ds_read_b128 v[216:219], v151 offset:6144
	ds_read_b128 v[240:243], v151 offset:7168
	global_load_lds_dwordx4 v[244:245], off
	v_lshl_add_u64 v[244:245], v[142:143], 0, v[136:137]
	s_add_i32 m0, s25, 0xe000
	s_nop 0
	global_load_lds_dwordx4 v[244:245], off
	s_waitcnt vmcnt(8)
	s_waitcnt lgkmcnt(0)
	s_barrier
; #define PG8_STAGE(bufoff, gbase, voff) do { _Pragma("unroll") for (int _i = 0; _i < 2; ++_i) \
;         __builtin_amdgcn_global_load_lds((const unsigned*)((const char*)(gbase) + (voff)[_i]), (LAS unsigned*)(lds + (bufoff) + ldsw + _i * 8192), 16, 0, 0); } while (0)
; #define PG8_LDA(dst, b, h) do { _Pragma("unroll") for (int m = 0; m < 4; ++m) _Pragma("unroll") for (int k = 0; k < 2; ++k) dst[m][k] = *(const LAS bf16x8*)(lds + PG8_SA(b, h) + aoff + m * 2048 + k * 1024); } while (0)
; #define PG8_MMA(ai, bj, At, Bt) do { __builtin_amdgcn_s_setprio(1); _Pragma("unroll") for (int k = 0; k < 2; ++k) _Pragma("unroll") for (int m = 0; m < 4; ++m) _Pragma("unroll") for (int n = 0; n < 2; ++n) \
;         acc[ai][bj][m][n] = __builtin_amdgcn_mfma_f32_16x16x32_bf16(Bt[n][k], At[m][k], acc[ai][bj][m][n], 0, 0, 0); __builtin_amdgcn_s_setprio(0); } while (0)
; #define PG8_WAIT_V(n) asm volatile("s_waitcnt vmcnt(" #n ")" ::: "memory")
; #define PG8_WAIT_L(n) asm volatile("s_waitcnt lgkmcnt(" #n ")" ::: "memory")
; #define PG8_BAR __builtin_amdgcn_s_barrier()
; #define PG8_SCHED __builtin_amdgcn_sched_barrier(0)
; template <class Epi, bool ALIGN_EPI>
; __device__ __forceinline__ void gemm_phase(LAS unsigned char* lds, const Gemm g, const StaticOrder& S, const Epi& E, const int tid) {
;     ...
;             PG8_WAIT_V(8); PG8_WAIT_L(0); PG8_BAR; PG8_MMA(0, 0, At, B0); PG8_MMA(0, 1, At, B1); PG8_BAR; PG8_SCHED;
;             PG8_LDA(At, 0, 1); PG8_STAGE(PG8_SB(0, 0), b2, voffB); PG8_STAGE(PG8_SB(0, 1), b2 + hB, voffB); PG8_STAGE(PG8_SA(0, 0), a2, voffA);
;             PG8_WAIT_V(8); PG8_WAIT_L(0); PG8_BAR; PG8_MMA(1, 0, At, B0); PG8_MMA(1, 1, At, B1); PG8_BAR; PG8_SCHED;
	s_setprio 1
	s_waitcnt lgkmcnt(0)
	v_mfma_f32_16x16x32_bf16 v[124:127], v[152:155], v[192:195], 0
	v_mfma_f32_16x16x32_bf16 v[120:123], v[160:163], v[192:195], 0
	v_mfma_f32_16x16x32_bf16 v[108:111], v[152:155], v[200:203], 0
	v_mfma_f32_16x16x32_bf16 v[104:107], v[160:163], v[200:203], 0
	v_mfma_f32_16x16x32_bf16 v[92:95], v[152:155], v[208:211], 0
	v_mfma_f32_16x16x32_bf16 v[88:91], v[160:163], v[208:211], 0
	v_mfma_f32_16x16x32_bf16 v[76:79], v[152:155], v[216:219], 0
	v_mfma_f32_16x16x32_bf16 v[72:75], v[160:163], v[216:219], 0
	v_mfma_f32_16x16x32_bf16 v[124:127], v[156:159], v[196:199], v[124:127]
	v_mfma_f32_16x16x32_bf16 v[120:123], v[164:167], v[196:199], v[120:123]
	v_mfma_f32_16x16x32_bf16 v[108:111], v[156:159], v[204:207], v[108:111]
	v_mfma_f32_16x16x32_bf16 v[104:107], v[164:167], v[204:207], v[104:107]
	v_mfma_f32_16x16x32_bf16 v[92:95], v[156:159], v[212:215], v[92:95]
	v_mfma_f32_16x16x32_bf16 v[88:91], v[164:167], v[212:215], v[88:91]
	v_mfma_f32_16x16x32_bf16 v[76:79], v[156:159], v[240:243], v[76:79]
	v_mfma_f32_16x16x32_bf16 v[72:75], v[164:167], v[240:243], v[72:75]
	s_setprio 0
	s_setprio 1
	v_mfma_f32_16x16x32_bf16 v[116:119], v[176:179], v[192:195], 0
	v_mfma_f32_16x16x32_bf16 v[112:115], v[184:187], v[192:195], 0
	v_mfma_f32_16x16x32_bf16 v[100:103], v[176:179], v[200:203], 0
	v_mfma_f32_16x16x32_bf16 v[96:99], v[184:187], v[200:203], 0
	v_mfma_f32_16x16x32_bf16 v[84:87], v[176:179], v[208:211], 0
	v_mfma_f32_16x16x32_bf16 v[80:83], v[184:187], v[208:211], 0
	v_mfma_f32_16x16x32_bf16 v[68:71], v[176:179], v[216:219], 0
	v_mfma_f32_16x16x32_bf16 v[64:67], v[184:187], v[216:219], 0
	v_mfma_f32_16x16x32_bf16 v[116:119], v[180:183], v[196:199], v[116:119]
	v_mfma_f32_16x16x32_bf16 v[112:115], v[188:191], v[196:199], v[112:115]
	v_mfma_f32_16x16x32_bf16 v[100:103], v[180:183], v[204:207], v[100:103]
	v_mfma_f32_16x16x32_bf16 v[96:99], v[188:191], v[204:207], v[96:99]
	v_mfma_f32_16x16x32_bf16 v[84:87], v[180:183], v[212:215], v[84:87]
	v_mfma_f32_16x16x32_bf16 v[80:83], v[188:191], v[212:215], v[80:83]
	v_mfma_f32_16x16x32_bf16 v[68:71], v[180:183], v[240:243], v[68:71]
	v_mfma_f32_16x16x32_bf16 v[64:67], v[188:191], v[240:243], v[64:67]
	s_setprio 0
	s_barrier
	s_add_i32 s62, s33, s45
	v_lshl_add_u64 v[244:245], v[220:221], 0, v[168:169]
	s_mov_b32 m0, s62
	ds_read_b128 v[192:195], v151 offset:16384
	ds_read_b128 v[196:199], v151 offset:17408
	ds_read_b128 v[200:203], v151 offset:18432
	ds_read_b128 v[204:207], v151 offset:19456
	ds_read_b128 v[208:211], v151 offset:20480
	ds_read_b128 v[212:215], v151 offset:21504
	ds_read_b128 v[216:219], v151 offset:22528
	ds_read_b128 v[240:243], v151 offset:23552
	global_load_lds_dwordx4 v[244:245], off
	v_lshl_add_u64 v[246:247], v[220:221], 0, v[128:129]
	s_add_i32 m0, s62, 0x2000
	v_lshl_add_u64 v[220:221], v[220:221], 0, s[12:13]
	s_add_i32 s10, s10, s45
	global_load_lds_dwordx4 v[246:247], off
	v_lshl_add_u64 v[248:249], v[220:221], 0, v[168:169]
	s_mov_b32 m0, s10
	v_lshl_add_u64 v[220:221], v[220:221], 0, v[128:129]
	global_load_lds_dwordx4 v[248:249], off
	s_add_i32 m0, s10, 0x2000
	v_lshl_add_u64 v[250:251], v[146:147], 0, v[132:133]
	global_load_lds_dwordx4 v[220:221], off
	s_mov_b32 m0, s25
	v_lshl_add_u64 v[252:253], v[146:147], 0, v[130:131]
	global_load_lds_dwordx4 v[250:251], off
	s_mov_b32 m0, s50
	s_nop 0
	global_load_lds_dwordx4 v[252:253], off
	s_waitcnt vmcnt(8)
	s_waitcnt lgkmcnt(0)
	s_barrier
	s_setprio 1
	s_waitcnt lgkmcnt(0)
	v_mfma_f32_16x16x32_bf16 v[60:63], v[152:155], v[192:195], 0
	v_mfma_f32_16x16x32_bf16 v[56:59], v[160:163], v[192:195], 0
	v_mfma_f32_16x16x32_bf16 v[44:47], v[152:155], v[200:203], 0
	v_mfma_f32_16x16x32_bf16 v[40:43], v[160:163], v[200:203], 0
	v_mfma_f32_16x16x32_bf16 v[28:31], v[152:155], v[208:211], 0
	v_mfma_f32_16x16x32_bf16 v[24:27], v[160:163], v[208:211], 0
	v_mfma_f32_16x16x32_bf16 v[12:15], v[152:155], v[216:219], 0
	v_mfma_f32_16x16x32_bf16 v[8:11], v[160:163], v[216:219], 0
	v_mfma_f32_16x16x32_bf16 v[60:63], v[156:159], v[196:199], v[60:63]
	v_mfma_f32_16x16x32_bf16 v[56:59], v[164:167], v[196:199], v[56:59]
	v_mfma_f32_16x16x32_bf16 v[44:47], v[156:159], v[204:207], v[44:47]
	v_mfma_f32_16x16x32_bf16 v[40:43], v[164:167], v[204:207], v[40:43]
	v_mfma_f32_16x16x32_bf16 v[28:31], v[156:159], v[212:215], v[28:31]
	v_mfma_f32_16x16x32_bf16 v[24:27], v[164:167], v[212:215], v[24:27]
	v_mfma_f32_16x16x32_bf16 v[12:15], v[156:159], v[240:243], v[12:15]
	v_mfma_f32_16x16x32_bf16 v[8:11], v[164:167], v[240:243], v[8:11]
	s_setprio 0
	s_setprio 1
	v_mfma_f32_16x16x32_bf16 v[52:55], v[176:179], v[192:195], 0
	v_mfma_f32_16x16x32_bf16 v[48:51], v[184:187], v[192:195], 0
	v_mfma_f32_16x16x32_bf16 v[36:39], v[176:179], v[200:203], 0
	v_mfma_f32_16x16x32_bf16 v[32:35], v[184:187], v[200:203], 0
	v_mfma_f32_16x16x32_bf16 v[20:23], v[176:179], v[208:211], 0
	v_mfma_f32_16x16x32_bf16 v[16:19], v[184:187], v[208:211], 0
	v_mfma_f32_16x16x32_bf16 v[4:7], v[176:179], v[216:219], 0
	v_mfma_f32_16x16x32_bf16 v[0:3], v[184:187], v[216:219], 0
	v_mfma_f32_16x16x32_bf16 v[52:55], v[180:183], v[196:199], v[52:55]
	v_mfma_f32_16x16x32_bf16 v[48:51], v[188:191], v[196:199], v[48:51]
	v_mfma_f32_16x16x32_bf16 v[36:39], v[180:183], v[204:207], v[36:39]
	v_mfma_f32_16x16x32_bf16 v[32:35], v[188:191], v[204:207], v[32:35]
	v_mfma_f32_16x16x32_bf16 v[20:23], v[180:183], v[212:215], v[20:23]
	v_mfma_f32_16x16x32_bf16 v[16:19], v[188:191], v[212:215], v[16:19]
	v_mfma_f32_16x16x32_bf16 v[4:7], v[180:183], v[240:243], v[4:7]
	v_mfma_f32_16x16x32_bf16 v[0:3], v[188:191], v[240:243], v[0:3]
	s_setprio 0
	s_barrier
; #define PG8_STAGE(bufoff, gbase, voff) do { _Pragma("unroll") for (int _i = 0; _i < 2; ++_i) \
;         __builtin_amdgcn_global_load_lds((const unsigned*)((const char*)(gbase) + (voff)[_i]), (LAS unsigned*)(lds + (bufoff) + ldsw + _i * 8192), 16, 0, 0); } while (0)
; #define PG8_LDA(dst, b, h) do { _Pragma("unroll") for (int m = 0; m < 4; ++m) _Pragma("unroll") for (int k = 0; k < 2; ++k) dst[m][k] = *(const LAS bf16x8*)(lds + PG8_SA(b, h) + aoff + m * 2048 + k * 1024); } while (0)
; #define PG8_LDB(dst, b, h) do { _Pragma("unroll") for (int n = 0; n < 2; ++n) _Pragma("unroll") for (int k = 0; k < 2; ++k) dst[n][k] = *(const LAS bf16x8*)(lds + PG8_SB(b, h) + boff + n * 2048 + k * 1024); } while (0)
; #define PG8_MMA(ai, bj, At, Bt) do { __builtin_amdgcn_s_setprio(1); _Pragma("unroll") for (int k = 0; k < 2; ++k) _Pragma("unroll") for (int m = 0; m < 4; ++m) _Pragma("unroll") for (int n = 0; n < 2; ++n) \
;         acc[ai][bj][m][n] = __builtin_amdgcn_mfma_f32_16x16x32_bf16(Bt[n][k], At[m][k], acc[ai][bj][m][n], 0, 0, 0); __builtin_amdgcn_s_setprio(0); } while (0)
; #define PG8_WAIT_V(n) asm volatile("s_waitcnt vmcnt(" #n ")" ::: "memory")
; #define PG8_WAIT_L(n) asm volatile("s_waitcnt lgkmcnt(" #n ")" ::: "memory")
; #define PG8_BAR __builtin_amdgcn_s_barrier()
; #define PG8_SCHED __builtin_amdgcn_sched_barrier(0)
; template <class Epi, bool ALIGN_EPI>
; __device__ __forceinline__ void gemm_phase(LAS unsigned char* lds, const Gemm g, const StaticOrder& S, const Epi& E, const int tid) {
;     ...
;             PG8_LDB(B0, 1, 0); PG8_LDB(B1, 1, 1); PG8_SCHED; PG8_LDA(At, 1, 0); PG8_STAGE(PG8_SA(0, 1), a2 + hA, voffA);
;             PG8_WAIT_V(8); PG8_WAIT_L(0); PG8_BAR; PG8_MMA(0, 0, At, B0); PG8_MMA(0, 1, At, B1); PG8_BAR; PG8_SCHED;
;             PG8_LDA(At, 1, 1); PG8_STAGE(PG8_SB(1, 0), b3, voffB); PG8_STAGE(PG8_SB(1, 1), b3 + hB, voffB); PG8_STAGE(PG8_SA(1, 0), a3, voffA);
	s_add_i32 s10, 0, 0x18000
	v_add_u32_e32 v148, s10, v149
	s_add_i32 s62, 0, 0x1c000
	ds_read_b128 v[152:155], v148
	ds_read_b128 v[156:159], v148 offset:1024
	ds_read_b128 v[160:163], v148 offset:2048
	ds_read_b128 v[164:167], v148 offset:3072
	v_add_u32_e32 v148, s62, v149
	ds_read_b128 v[176:179], v148
	ds_read_b128 v[180:183], v148 offset:1024
	ds_read_b128 v[184:187], v148 offset:2048
	ds_read_b128 v[188:191], v148 offset:3072
	v_lshl_add_u64 v[146:147], v[146:147], 0, s[94:95]
	s_mov_b32 m0, s51
	v_lshl_add_u64 v[226:227], v[146:147], 0, v[132:133]
	ds_read_b128 v[192:195], v151 offset:32768
	ds_read_b128 v[196:199], v151 offset:33792
	ds_read_b128 v[200:203], v151 offset:34816
	ds_read_b128 v[204:207], v151 offset:35840
	ds_read_b128 v[208:211], v151 offset:36864
	ds_read_b128 v[212:215], v151 offset:37888
	ds_read_b128 v[216:219], v151 offset:38912
	ds_read_b128 v[240:243], v151 offset:39936
	global_load_lds_dwordx4 v[226:227], off
	v_lshl_add_u64 v[146:147], v[146:147], 0, v[130:131]
	s_mov_b32 m0, s52
	s_nop 0
	global_load_lds_dwordx4 v[146:147], off
	s_waitcnt vmcnt(8)
	s_waitcnt lgkmcnt(0)
	s_barrier
	s_setprio 1
	s_waitcnt lgkmcnt(0)
	v_mfma_f32_16x16x32_bf16 v[124:127], v[152:155], v[192:195], v[124:127]
	v_mfma_f32_16x16x32_bf16 v[120:123], v[160:163], v[192:195], v[120:123]
	v_mfma_f32_16x16x32_bf16 v[108:111], v[152:155], v[200:203], v[108:111]
	v_mfma_f32_16x16x32_bf16 v[104:107], v[160:163], v[200:203], v[104:107]
	v_mfma_f32_16x16x32_bf16 v[92:95], v[152:155], v[208:211], v[92:95]
	v_mfma_f32_16x16x32_bf16 v[88:91], v[160:163], v[208:211], v[88:91]
	v_mfma_f32_16x16x32_bf16 v[76:79], v[152:155], v[216:219], v[76:79]
	v_mfma_f32_16x16x32_bf16 v[72:75], v[160:163], v[216:219], v[72:75]
	v_mfma_f32_16x16x32_bf16 v[124:127], v[156:159], v[196:199], v[124:127]
	v_mfma_f32_16x16x32_bf16 v[120:123], v[164:167], v[196:199], v[120:123]
	v_mfma_f32_16x16x32_bf16 v[108:111], v[156:159], v[204:207], v[108:111]
	v_mfma_f32_16x16x32_bf16 v[104:107], v[164:167], v[204:207], v[104:107]
	v_mfma_f32_16x16x32_bf16 v[92:95], v[156:159], v[212:215], v[92:95]
	v_mfma_f32_16x16x32_bf16 v[88:91], v[164:167], v[212:215], v[88:91]
	v_mfma_f32_16x16x32_bf16 v[76:79], v[156:159], v[240:243], v[76:79]
	v_mfma_f32_16x16x32_bf16 v[72:75], v[164:167], v[240:243], v[72:75]
	s_setprio 0
	s_setprio 1
	v_mfma_f32_16x16x32_bf16 v[116:119], v[176:179], v[192:195], v[116:119]
	v_mfma_f32_16x16x32_bf16 v[112:115], v[184:187], v[192:195], v[112:115]
	v_mfma_f32_16x16x32_bf16 v[100:103], v[176:179], v[200:203], v[100:103]
	v_mfma_f32_16x16x32_bf16 v[96:99], v[184:187], v[200:203], v[96:99]
	v_mfma_f32_16x16x32_bf16 v[84:87], v[176:179], v[208:211], v[84:87]
	v_mfma_f32_16x16x32_bf16 v[80:83], v[184:187], v[208:211], v[80:83]
	v_mfma_f32_16x16x32_bf16 v[68:71], v[176:179], v[216:219], v[68:71]
	v_mfma_f32_16x16x32_bf16 v[64:67], v[184:187], v[216:219], v[64:67]
	v_mfma_f32_16x16x32_bf16 v[116:119], v[180:183], v[196:199], v[116:119]
	v_mfma_f32_16x16x32_bf16 v[112:115], v[188:191], v[196:199], v[112:115]
	v_mfma_f32_16x16x32_bf16 v[100:103], v[180:183], v[204:207], v[100:103]
	v_mfma_f32_16x16x32_bf16 v[96:99], v[188:191], v[204:207], v[96:99]
	v_mfma_f32_16x16x32_bf16 v[84:87], v[180:183], v[212:215], v[84:87]
	v_mfma_f32_16x16x32_bf16 v[80:83], v[188:191], v[212:215], v[80:83]
	v_mfma_f32_16x16x32_bf16 v[68:71], v[180:183], v[240:243], v[68:71]
	v_mfma_f32_16x16x32_bf16 v[64:67], v[188:191], v[240:243], v[64:67]
	s_setprio 0
	s_barrier
	s_add_i32 s10, s10, s45
	v_lshl_add_u64 v[146:147], v[244:245], 0, s[92:93]
	s_mov_b32 m0, s10
	ds_read_b128 v[192:195], v151 offset:49152
	ds_read_b128 v[196:199], v151 offset:50176
	ds_read_b128 v[200:203], v151 offset:51200
	ds_read_b128 v[204:207], v151 offset:52224
	ds_read_b128 v[208:211], v151 offset:53248
	ds_read_b128 v[212:215], v151 offset:54272
	ds_read_b128 v[216:219], v151 offset:55296
	ds_read_b128 v[240:243], v151 offset:56320
	global_load_lds_dwordx4 v[146:147], off
	v_lshl_add_u64 v[146:147], v[246:247], 0, s[92:93]
	s_add_i32 m0, s10, 0x2000
	s_add_i32 s10, s62, s45
	global_load_lds_dwordx4 v[146:147], off
	v_lshl_add_u64 v[146:147], v[248:249], 0, s[92:93]
	s_mov_b32 m0, s10
	s_nop 0
	global_load_lds_dwordx4 v[146:147], off
	v_lshl_add_u64 v[146:147], v[220:221], 0, s[92:93]
	s_add_i32 m0, s10, 0x2000
	s_nop 0
	global_load_lds_dwordx4 v[146:147], off
	v_lshl_add_u64 v[146:147], v[250:251], 0, s[92:93]
	s_mov_b32 m0, s53
	s_nop 0
	global_load_lds_dwordx4 v[146:147], off
	v_lshl_add_u64 v[146:147], v[252:253], 0, s[92:93]
	s_mov_b32 m0, s54
	s_nop 0
	global_load_lds_dwordx4 v[146:147], off
	s_waitcnt vmcnt(8)
	s_waitcnt lgkmcnt(0)
	s_barrier
; #define PG8_STAGE(bufoff, gbase, voff) do { _Pragma("unroll") for (int _i = 0; _i < 2; ++_i) \
;         __builtin_amdgcn_global_load_lds((const unsigned*)((const char*)(gbase) + (voff)[_i]), (LAS unsigned*)(lds + (bufoff) + ldsw + _i * 8192), 16, 0, 0); } while (0)
; #define PG8_LDA(dst, b, h) do { _Pragma("unroll") for (int m = 0; m < 4; ++m) _Pragma("unroll") for (int k = 0; k < 2; ++k) dst[m][k] = *(const LAS bf16x8*)(lds + PG8_SA(b, h) + aoff + m * 2048 + k * 1024); } while (0)
; #define PG8_LDB(dst, b, h) do { _Pragma("unroll") for (int n = 0; n < 2; ++n) _Pragma("unroll") for (int k = 0; k < 2; ++k) dst[n][k] = *(const LAS bf16x8*)(lds + PG8_SB(b, h) + boff + n * 2048 + k * 1024); } while (0)
; #define PG8_MMA(ai, bj, At, Bt) do { __builtin_amdgcn_s_setprio(1); _Pragma("unroll") for (int k = 0; k < 2; ++k) _Pragma("unroll") for (int m = 0; m < 4; ++m) _Pragma("unroll") for (int n = 0; n < 2; ++n) \
;         acc[ai][bj][m][n] = __builtin_amdgcn_mfma_f32_16x16x32_bf16(Bt[n][k], At[m][k], acc[ai][bj][m][n], 0, 0, 0); __builtin_amdgcn_s_setprio(0); } while (0)
; #define PG8_WAIT_V(n) asm volatile("s_waitcnt vmcnt(" #n ")" ::: "memory")
; #define PG8_WAIT_L(n) asm volatile("s_waitcnt lgkmcnt(" #n ")" ::: "memory")
; #define PG8_BAR __builtin_amdgcn_s_barrier()
; #define PG8_SCHED __builtin_amdgcn_sched_barrier(0)
; template <class Epi, bool ALIGN_EPI>
; __device__ __forceinline__ void gemm_phase(LAS unsigned char* lds, const Gemm g, const StaticOrder& S, const Epi& E, const int tid) {
;     ...
;             PG8_LDB(B0, 0, 0); PG8_LDB(B1, 0, 1); PG8_SCHED; PG8_LDA(At, 0, 0); PG8_STAGE(PG8_SA(1, 1), a1 + hA, voffA);
;             PG8_WAIT_V(8); PG8_WAIT_L(0); PG8_BAR; PG8_MMA(0, 0, At, B0); PG8_MMA(0, 1, At, B1); PG8_BAR; PG8_SCHED;
;     ...
;             PG8_WAIT_V(8); PG8_WAIT_L(0); PG8_BAR; PG8_MMA(1, 0, At, B0); PG8_MMA(1, 1, At, B1); PG8_BAR; PG8_SCHED;
	s_setprio 1
	s_waitcnt lgkmcnt(0)
	v_mfma_f32_16x16x32_bf16 v[60:63], v[152:155], v[192:195], v[60:63]
	v_mfma_f32_16x16x32_bf16 v[56:59], v[160:163], v[192:195], v[56:59]
	v_mfma_f32_16x16x32_bf16 v[44:47], v[152:155], v[200:203], v[44:47]
	v_mfma_f32_16x16x32_bf16 v[40:43], v[160:163], v[200:203], v[40:43]
	v_mfma_f32_16x16x32_bf16 v[28:31], v[152:155], v[208:211], v[28:31]
	v_mfma_f32_16x16x32_bf16 v[24:27], v[160:163], v[208:211], v[24:27]
	v_mfma_f32_16x16x32_bf16 v[12:15], v[152:155], v[216:219], v[12:15]
	v_mfma_f32_16x16x32_bf16 v[8:11], v[160:163], v[216:219], v[8:11]
	v_mfma_f32_16x16x32_bf16 v[60:63], v[156:159], v[196:199], v[60:63]
	v_mfma_f32_16x16x32_bf16 v[56:59], v[164:167], v[196:199], v[56:59]
	v_mfma_f32_16x16x32_bf16 v[44:47], v[156:159], v[204:207], v[44:47]
	v_mfma_f32_16x16x32_bf16 v[40:43], v[164:167], v[204:207], v[40:43]
	v_mfma_f32_16x16x32_bf16 v[28:31], v[156:159], v[212:215], v[28:31]
	v_mfma_f32_16x16x32_bf16 v[24:27], v[164:167], v[212:215], v[24:27]
	v_mfma_f32_16x16x32_bf16 v[12:15], v[156:159], v[240:243], v[12:15]
	v_mfma_f32_16x16x32_bf16 v[8:11], v[164:167], v[240:243], v[8:11]
	s_setprio 0
	s_setprio 1
	v_mfma_f32_16x16x32_bf16 v[52:55], v[176:179], v[192:195], v[52:55]
	v_mfma_f32_16x16x32_bf16 v[48:51], v[184:187], v[192:195], v[48:51]
	v_mfma_f32_16x16x32_bf16 v[36:39], v[176:179], v[200:203], v[36:39]
	v_mfma_f32_16x16x32_bf16 v[32:35], v[184:187], v[200:203], v[32:35]
	v_mfma_f32_16x16x32_bf16 v[20:23], v[176:179], v[208:211], v[20:23]
	v_mfma_f32_16x16x32_bf16 v[16:19], v[184:187], v[208:211], v[16:19]
	v_mfma_f32_16x16x32_bf16 v[4:7], v[176:179], v[216:219], v[4:7]
	v_mfma_f32_16x16x32_bf16 v[0:3], v[184:187], v[216:219], v[0:3]
	v_mfma_f32_16x16x32_bf16 v[52:55], v[180:183], v[196:199], v[52:55]
	v_mfma_f32_16x16x32_bf16 v[48:51], v[188:191], v[196:199], v[48:51]
	v_mfma_f32_16x16x32_bf16 v[36:39], v[180:183], v[204:207], v[36:39]
	v_mfma_f32_16x16x32_bf16 v[32:35], v[188:191], v[204:207], v[32:35]
	v_mfma_f32_16x16x32_bf16 v[20:23], v[180:183], v[212:215], v[20:23]
	v_mfma_f32_16x16x32_bf16 v[16:19], v[188:191], v[212:215], v[16:19]
	v_mfma_f32_16x16x32_bf16 v[4:7], v[180:183], v[240:243], v[4:7]
	v_mfma_f32_16x16x32_bf16 v[0:3], v[188:191], v[240:243], v[0:3]
	s_setprio 0
	s_barrier
	v_lshl_add_u64 v[142:143], v[142:143], 0, s[80:81]
	v_lshl_add_u64 v[144:145], v[144:145], 0, s[80:81]
	s_mov_b32 s10, s11
	s_cmp_eq_u32 s10, s55
	s_cbranch_scc1 .Lq5_last
.LBB0_354:
	s_add_i32 s11, s10, 2
	s_cmp_eq_u32 s55, s10
	s_cselect_b64 vcc, -1, 0
	v_add_u32_e32 v148, s33, v149
	s_add_i32 s10, 0, 0x14000
	ds_read_b128 v[152:155], v148
	ds_read_b128 v[156:159], v148 offset:1024
	ds_read_b128 v[160:163], v148 offset:2048
	ds_read_b128 v[164:167], v148 offset:3072
	v_add_u32_e32 v148, s10, v149
	ds_read_b128 v[176:179], v148
	ds_read_b128 v[180:183], v148 offset:1024
	ds_read_b128 v[184:187], v148 offset:2048
	ds_read_b128 v[188:191], v148 offset:3072
	v_lshl_add_u64 v[146:147], v[142:143], 0, s[92:93]
	v_cndmask_b32_e32 v147, v147, v139, vcc
	v_cndmask_b32_e32 v146, v146, v138, vcc
	v_cndmask_b32_e32 v221, v145, v141, vcc
	v_cndmask_b32_e32 v220, v144, v140, vcc
	v_lshl_add_u64 v[244:245], v[142:143], 0, v[134:135]
	s_add_i32 m0, s25, 0xc000
	ds_read_b128 v[192:195], v151
	ds_read_b128 v[196:199], v151 offset:1024
	ds_read_b128 v[200:203], v151 offset:2048
	ds_read_b128 v[204:207], v151 offset:3072
	ds_read_b128 v[208:211], v151 offset:4096
	ds_read_b128 v[212:215], v151 offset:5120
	ds_read_b128 v[216:219], v151 offset:6144
	ds_read_b128 v[240:243], v151 offset:7168
	global_load_lds_dwordx4 v[244:245], off
	v_lshl_add_u64 v[244:245], v[142:143], 0, v[136:137]
	s_add_i32 m0, s25, 0xe000
	s_nop 0
	global_load_lds_dwordx4 v[244:245], off
	s_waitcnt vmcnt(8)
	s_waitcnt lgkmcnt(0)
	s_barrier
	s_setprio 1
	s_waitcnt lgkmcnt(0)
	v_mfma_f32_16x16x32_bf16 v[124:127], v[152:155], v[192:195], v[124:127]
	v_mfma_f32_16x16x32_bf16 v[120:123], v[160:163], v[192:195], v[120:123]
	v_mfma_f32_16x16x32_bf16 v[108:111], v[152:155], v[200:203], v[108:111]
	v_mfma_f32_16x16x32_bf16 v[104:107], v[160:163], v[200:203], v[104:107]
	v_mfma_f32_16x16x32_bf16 v[92:95], v[152:155], v[208:211], v[92:95]
	v_mfma_f32_16x16x32_bf16 v[88:91], v[160:163], v[208:211], v[88:91]
	v_mfma_f32_16x16x32_bf16 v[76:79], v[152:155], v[216:219], v[76:79]
	v_mfma_f32_16x16x32_bf16 v[72:75], v[160:163], v[216:219], v[72:75]
	v_mfma_f32_16x16x32_bf16 v[124:127], v[156:159], v[196:199], v[124:127]
	v_mfma_f32_16x16x32_bf16 v[120:123], v[164:167], v[196:199], v[120:123]
	v_mfma_f32_16x16x32_bf16 v[108:111], v[156:159], v[204:207], v[108:111]
	v_mfma_f32_16x16x32_bf16 v[104:107], v[164:167], v[204:207], v[104:107]
	v_mfma_f32_16x16x32_bf16 v[92:95], v[156:159], v[212:215], v[92:95]
	v_mfma_f32_16x16x32_bf16 v[88:91], v[164:167], v[212:215], v[88:91]
	v_mfma_f32_16x16x32_bf16 v[76:79], v[156:159], v[240:243], v[76:79]
	v_mfma_f32_16x16x32_bf16 v[72:75], v[164:167], v[240:243], v[72:75]
	s_setprio 0
	s_setprio 1
	v_mfma_f32_16x16x32_bf16 v[116:119], v[176:179], v[192:195], v[116:119]
	v_mfma_f32_16x16x32_bf16 v[112:115], v[184:187], v[192:195], v[112:115]
	v_mfma_f32_16x16x32_bf16 v[100:103], v[176:179], v[200:203], v[100:103]
	v_mfma_f32_16x16x32_bf16 v[96:99], v[184:187], v[200:203], v[96:99]
	v_mfma_f32_16x16x32_bf16 v[84:87], v[176:179], v[208:211], v[84:87]
	v_mfma_f32_16x16x32_bf16 v[80:83], v[184:187], v[208:211], v[80:83]
	v_mfma_f32_16x16x32_bf16 v[68:71], v[176:179], v[216:219], v[68:71]
	v_mfma_f32_16x16x32_bf16 v[64:67], v[184:187], v[216:219], v[64:67]
	v_mfma_f32_16x16x32_bf16 v[116:119], v[180:183], v[196:199], v[116:119]
	v_mfma_f32_16x16x32_bf16 v[112:115], v[188:191], v[196:199], v[112:115]
	v_mfma_f32_16x16x32_bf16 v[100:103], v[180:183], v[204:207], v[100:103]
	v_mfma_f32_16x16x32_bf16 v[96:99], v[188:191], v[204:207], v[96:99]
	v_mfma_f32_16x16x32_bf16 v[84:87], v[180:183], v[212:215], v[84:87]
	v_mfma_f32_16x16x32_bf16 v[80:83], v[188:191], v[212:215], v[80:83]
	v_mfma_f32_16x16x32_bf16 v[68:71], v[180:183], v[240:243], v[68:71]
	v_mfma_f32_16x16x32_bf16 v[64:67], v[188:191], v[240:243], v[64:67]
	s_setprio 0
	s_barrier
; #define PG8_STAGE(bufoff, gbase, voff) do { _Pragma("unroll") for (int _i = 0; _i < 2; ++_i) \
;         __builtin_amdgcn_global_load_lds((const unsigned*)((const char*)(gbase) + (voff)[_i]), (LAS unsigned*)(lds + (bufoff) + ldsw + _i * 8192), 16, 0, 0); } while (0)
; #define PG8_LDA(dst, b, h) do { _Pragma("unroll") for (int m = 0; m < 4; ++m) _Pragma("unroll") for (int k = 0; k < 2; ++k) dst[m][k] = *(const LAS bf16x8*)(lds + PG8_SA(b, h) + aoff + m * 2048 + k * 1024); } while (0)
; #define PG8_LDB(dst, b, h) do { _Pragma("unroll") for (int n = 0; n < 2; ++n) _Pragma("unroll") for (int k = 0; k < 2; ++k) dst[n][k] = *(const LAS bf16x8*)(lds + PG8_SB(b, h) + boff + n * 2048 + k * 1024); } while (0)
; #define PG8_MMA(ai, bj, At, Bt) do { __builtin_amdgcn_s_setprio(1); _Pragma("unroll") for (int k = 0; k < 2; ++k) _Pragma("unroll") for (int m = 0; m < 4; ++m) _Pragma("unroll") for (int n = 0; n < 2; ++n) \
;         acc[ai][bj][m][n] = __builtin_amdgcn_mfma_f32_16x16x32_bf16(Bt[n][k], At[m][k], acc[ai][bj][m][n], 0, 0, 0); __builtin_amdgcn_s_setprio(0); } while (0)
; #define PG8_WAIT_V(n) asm volatile("s_waitcnt vmcnt(" #n ")" ::: "memory")
; #define PG8_WAIT_L(n) asm volatile("s_waitcnt lgkmcnt(" #n ")" ::: "memory")
; #define PG8_BAR __builtin_amdgcn_s_barrier()
; #define PG8_SCHED __builtin_amdgcn_sched_barrier(0)
; template <class Epi, bool ALIGN_EPI>
; __device__ __forceinline__ void gemm_phase(LAS unsigned char* lds, const Gemm g, const StaticOrder& S, const Epi& E, const int tid) {
;     ...
;             PG8_LDA(At, 0, 1); PG8_STAGE(PG8_SB(0, 0), b2, voffB); PG8_STAGE(PG8_SB(0, 1), b2 + hB, voffB); PG8_STAGE(PG8_SA(0, 0), a2, voffA);
;             PG8_WAIT_V(8); PG8_WAIT_L(0); PG8_BAR; PG8_MMA(1, 0, At, B0); PG8_MMA(1, 1, At, B1); PG8_BAR; PG8_SCHED;
;             PG8_LDB(B0, 1, 0); PG8_LDB(B1, 1, 1); PG8_SCHED; PG8_LDA(At, 1, 0); PG8_STAGE(PG8_SA(0, 1), a2 + hA, voffA);
;             PG8_WAIT_V(8); PG8_WAIT_L(0); PG8_BAR; PG8_MMA(0, 0, At, B0); PG8_MMA(0, 1, At, B1); PG8_BAR; PG8_SCHED;
;             PG8_LDA(At, 1, 1); PG8_STAGE(PG8_SB(1, 0), b3, voffB); PG8_STAGE(PG8_SB(1, 1), b3 + hB, voffB); PG8_STAGE(PG8_SA(1, 0), a3, voffA);
	s_add_i32 s62, s33, s45
	v_lshl_add_u64 v[244:245], v[220:221], 0, v[168:169]
	s_mov_b32 m0, s62
	ds_read_b128 v[192:195], v151 offset:16384
	ds_read_b128 v[196:199], v151 offset:17408
	ds_read_b128 v[200:203], v151 offset:18432
	ds_read_b128 v[204:207], v151 offset:19456
	ds_read_b128 v[208:211], v151 offset:20480
	ds_read_b128 v[212:215], v151 offset:21504
	ds_read_b128 v[216:219], v151 offset:22528
	ds_read_b128 v[240:243], v151 offset:23552
	global_load_lds_dwordx4 v[244:245], off
	v_lshl_add_u64 v[246:247], v[220:221], 0, v[128:129]
	s_add_i32 m0, s62, 0x2000
	v_lshl_add_u64 v[220:221], v[220:221], 0, s[12:13]
	s_add_i32 s10, s10, s45
	global_load_lds_dwordx4 v[246:247], off
	v_lshl_add_u64 v[248:249], v[220:221], 0, v[168:169]
	s_mov_b32 m0, s10
	v_lshl_add_u64 v[220:221], v[220:221], 0, v[128:129]
	global_load_lds_dwordx4 v[248:249], off
	s_add_i32 m0, s10, 0x2000
	v_lshl_add_u64 v[250:251], v[146:147], 0, v[132:133]
	global_load_lds_dwordx4 v[220:221], off
	s_mov_b32 m0, s25
	v_lshl_add_u64 v[252:253], v[146:147], 0, v[130:131]
	global_load_lds_dwordx4 v[250:251], off
	s_mov_b32 m0, s50
	s_nop 0
	global_load_lds_dwordx4 v[252:253], off
	s_waitcnt vmcnt(8)
	s_waitcnt lgkmcnt(0)
	s_barrier
	s_setprio 1
	s_waitcnt lgkmcnt(0)
	v_mfma_f32_16x16x32_bf16 v[60:63], v[152:155], v[192:195], v[60:63]
	v_mfma_f32_16x16x32_bf16 v[56:59], v[160:163], v[192:195], v[56:59]
	v_mfma_f32_16x16x32_bf16 v[44:47], v[152:155], v[200:203], v[44:47]
	v_mfma_f32_16x16x32_bf16 v[40:43], v[160:163], v[200:203], v[40:43]
	v_mfma_f32_16x16x32_bf16 v[28:31], v[152:155], v[208:211], v[28:31]
	v_mfma_f32_16x16x32_bf16 v[24:27], v[160:163], v[208:211], v[24:27]
	v_mfma_f32_16x16x32_bf16 v[12:15], v[152:155], v[216:219], v[12:15]
	v_mfma_f32_16x16x32_bf16 v[8:11], v[160:163], v[216:219], v[8:11]
	v_mfma_f32_16x16x32_bf16 v[60:63], v[156:159], v[196:199], v[60:63]
	v_mfma_f32_16x16x32_bf16 v[56:59], v[164:167], v[196:199], v[56:59]
	v_mfma_f32_16x16x32_bf16 v[44:47], v[156:159], v[204:207], v[44:47]
	v_mfma_f32_16x16x32_bf16 v[40:43], v[164:167], v[204:207], v[40:43]
	v_mfma_f32_16x16x32_bf16 v[28:31], v[156:159], v[212:215], v[28:31]
	v_mfma_f32_16x16x32_bf16 v[24:27], v[164:167], v[212:215], v[24:27]
	v_mfma_f32_16x16x32_bf16 v[12:15], v[156:159], v[240:243], v[12:15]
	v_mfma_f32_16x16x32_bf16 v[8:11], v[164:167], v[240:243], v[8:11]
	s_setprio 0
	s_setprio 1
	v_mfma_f32_16x16x32_bf16 v[52:55], v[176:179], v[192:195], v[52:55]
	v_mfma_f32_16x16x32_bf16 v[48:51], v[184:187], v[192:195], v[48:51]
	v_mfma_f32_16x16x32_bf16 v[36:39], v[176:179], v[200:203], v[36:39]
	v_mfma_f32_16x16x32_bf16 v[32:35], v[184:187], v[200:203], v[32:35]
	v_mfma_f32_16x16x32_bf16 v[20:23], v[176:179], v[208:211], v[20:23]
	v_mfma_f32_16x16x32_bf16 v[16:19], v[184:187], v[208:211], v[16:19]
	v_mfma_f32_16x16x32_bf16 v[4:7], v[176:179], v[216:219], v[4:7]
	v_mfma_f32_16x16x32_bf16 v[0:3], v[184:187], v[216:219], v[0:3]
	v_mfma_f32_16x16x32_bf16 v[52:55], v[180:183], v[196:199], v[52:55]
	v_mfma_f32_16x16x32_bf16 v[48:51], v[188:191], v[196:199], v[48:51]
	v_mfma_f32_16x16x32_bf16 v[36:39], v[180:183], v[204:207], v[36:39]
	v_mfma_f32_16x16x32_bf16 v[32:35], v[188:191], v[204:207], v[32:35]
	v_mfma_f32_16x16x32_bf16 v[20:23], v[180:183], v[212:215], v[20:23]
	v_mfma_f32_16x16x32_bf16 v[16:19], v[188:191], v[212:215], v[16:19]
	v_mfma_f32_16x16x32_bf16 v[4:7], v[180:183], v[240:243], v[4:7]
	v_mfma_f32_16x16x32_bf16 v[0:3], v[188:191], v[240:243], v[0:3]
	s_setprio 0
	s_barrier
	s_add_i32 s10, 0, 0x18000
	v_add_u32_e32 v148, s10, v149
	s_add_i32 s62, 0, 0x1c000
	ds_read_b128 v[152:155], v148
	ds_read_b128 v[156:159], v148 offset:1024
	ds_read_b128 v[160:163], v148 offset:2048
	ds_read_b128 v[164:167], v148 offset:3072
	v_add_u32_e32 v148, s62, v149
	ds_read_b128 v[176:179], v148
	ds_read_b128 v[180:183], v148 offset:1024
	ds_read_b128 v[184:187], v148 offset:2048
	ds_read_b128 v[188:191], v148 offset:3072
	v_lshl_add_u64 v[146:147], v[146:147], 0, s[94:95]
	s_mov_b32 m0, s51
	v_lshl_add_u64 v[226:227], v[146:147], 0, v[132:133]
	ds_read_b128 v[192:195], v151 offset:32768
	ds_read_b128 v[196:199], v151 offset:33792
	ds_read_b128 v[200:203], v151 offset:34816
	ds_read_b128 v[204:207], v151 offset:35840
	ds_read_b128 v[208:211], v151 offset:36864
	ds_read_b128 v[212:215], v151 offset:37888
	ds_read_b128 v[216:219], v151 offset:38912
	ds_read_b128 v[240:243], v151 offset:39936
	global_load_lds_dwordx4 v[226:227], off
	v_lshl_add_u64 v[146:147], v[146:147], 0, v[130:131]
	s_mov_b32 m0, s52
	s_nop 0
	global_load_lds_dwordx4 v[146:147], off
	s_waitcnt vmcnt(8)
	s_waitcnt lgkmcnt(0)
	s_barrier
; #define PG8_STAGE(bufoff, gbase, voff) do { _Pragma("unroll") for (int _i = 0; _i < 2; ++_i) \
;         __builtin_amdgcn_global_load_lds((const unsigned*)((const char*)(gbase) + (voff)[_i]), (LAS unsigned*)(lds + (bufoff) + ldsw + _i * 8192), 16, 0, 0); } while (0)
; #define PG8_LDA(dst, b, h) do { _Pragma("unroll") for (int m = 0; m < 4; ++m) _Pragma("unroll") for (int k = 0; k < 2; ++k) dst[m][k] = *(const LAS bf16x8*)(lds + PG8_SA(b, h) + aoff + m * 2048 + k * 1024); } while (0)
; #define PG8_MMA(ai, bj, At, Bt) do { __builtin_amdgcn_s_setprio(1); _Pragma("unroll") for (int k = 0; k < 2; ++k) _Pragma("unroll") for (int m = 0; m < 4; ++m) _Pragma("unroll") for (int n = 0; n < 2; ++n) \
;         acc[ai][bj][m][n] = __builtin_amdgcn_mfma_f32_16x16x32_bf16(Bt[n][k], At[m][k], acc[ai][bj][m][n], 0, 0, 0); __builtin_amdgcn_s_setprio(0); } while (0)
; #define PG8_WAIT_V(n) asm volatile("s_waitcnt vmcnt(" #n ")" ::: "memory")
; #define PG8_WAIT_L(n) asm volatile("s_waitcnt lgkmcnt(" #n ")" ::: "memory")
; #define PG8_BAR __builtin_amdgcn_s_barrier()
; #define PG8_SCHED __builtin_amdgcn_sched_barrier(0)
; template <class Epi, bool ALIGN_EPI>
; __device__ __forceinline__ void gemm_phase(LAS unsigned char* lds, const Gemm g, const StaticOrder& S, const Epi& E, const int tid) {
;     ...
;         for (int t = 0; t < nt; t += 2) {
;     ...
;             PG8_WAIT_V(8); PG8_WAIT_L(0); PG8_BAR; PG8_MMA(0, 0, At, B0); PG8_MMA(0, 1, At, B1); PG8_BAR; PG8_SCHED;
;             PG8_LDA(At, 1, 1); PG8_STAGE(PG8_SB(1, 0), b3, voffB); PG8_STAGE(PG8_SB(1, 1), b3 + hB, voffB); PG8_STAGE(PG8_SA(1, 0), a3, voffA);
;             PG8_WAIT_V(8); PG8_WAIT_L(0); PG8_BAR; PG8_MMA(1, 0, At, B0); PG8_MMA(1, 1, At, B1); PG8_BAR; PG8_SCHED;
	s_setprio 1
	s_waitcnt lgkmcnt(0)
	v_mfma_f32_16x16x32_bf16 v[124:127], v[152:155], v[192:195], v[124:127]
	v_mfma_f32_16x16x32_bf16 v[120:123], v[160:163], v[192:195], v[120:123]
	v_mfma_f32_16x16x32_bf16 v[108:111], v[152:155], v[200:203], v[108:111]
	v_mfma_f32_16x16x32_bf16 v[104:107], v[160:163], v[200:203], v[104:107]
	v_mfma_f32_16x16x32_bf16 v[92:95], v[152:155], v[208:211], v[92:95]
	v_mfma_f32_16x16x32_bf16 v[88:91], v[160:163], v[208:211], v[88:91]
	v_mfma_f32_16x16x32_bf16 v[76:79], v[152:155], v[216:219], v[76:79]
	v_mfma_f32_16x16x32_bf16 v[72:75], v[160:163], v[216:219], v[72:75]
	v_mfma_f32_16x16x32_bf16 v[124:127], v[156:159], v[196:199], v[124:127]
	v_mfma_f32_16x16x32_bf16 v[120:123], v[164:167], v[196:199], v[120:123]
	v_mfma_f32_16x16x32_bf16 v[108:111], v[156:159], v[204:207], v[108:111]
	v_mfma_f32_16x16x32_bf16 v[104:107], v[164:167], v[204:207], v[104:107]
	v_mfma_f32_16x16x32_bf16 v[92:95], v[156:159], v[212:215], v[92:95]
	v_mfma_f32_16x16x32_bf16 v[88:91], v[164:167], v[212:215], v[88:91]
	v_mfma_f32_16x16x32_bf16 v[76:79], v[156:159], v[240:243], v[76:79]
	v_mfma_f32_16x16x32_bf16 v[72:75], v[164:167], v[240:243], v[72:75]
	s_setprio 0
	s_setprio 1
	v_mfma_f32_16x16x32_bf16 v[116:119], v[176:179], v[192:195], v[116:119]
	v_mfma_f32_16x16x32_bf16 v[112:115], v[184:187], v[192:195], v[112:115]
	v_mfma_f32_16x16x32_bf16 v[100:103], v[176:179], v[200:203], v[100:103]
	v_mfma_f32_16x16x32_bf16 v[96:99], v[184:187], v[200:203], v[96:99]
	v_mfma_f32_16x16x32_bf16 v[84:87], v[176:179], v[208:211], v[84:87]
	v_mfma_f32_16x16x32_bf16 v[80:83], v[184:187], v[208:211], v[80:83]
	v_mfma_f32_16x16x32_bf16 v[68:71], v[176:179], v[216:219], v[68:71]
	v_mfma_f32_16x16x32_bf16 v[64:67], v[184:187], v[216:219], v[64:67]
	v_mfma_f32_16x16x32_bf16 v[116:119], v[180:183], v[196:199], v[116:119]
	v_mfma_f32_16x16x32_bf16 v[112:115], v[188:191], v[196:199], v[112:115]
	v_mfma_f32_16x16x32_bf16 v[100:103], v[180:183], v[204:207], v[100:103]
	v_mfma_f32_16x16x32_bf16 v[96:99], v[188:191], v[204:207], v[96:99]
	v_mfma_f32_16x16x32_bf16 v[84:87], v[180:183], v[212:215], v[84:87]
	v_mfma_f32_16x16x32_bf16 v[80:83], v[188:191], v[212:215], v[80:83]
	v_mfma_f32_16x16x32_bf16 v[68:71], v[180:183], v[240:243], v[68:71]
	v_mfma_f32_16x16x32_bf16 v[64:67], v[188:191], v[240:243], v[64:67]
	s_setprio 0
	s_barrier
	s_add_i32 s10, s10, s45
	v_lshl_add_u64 v[146:147], v[244:245], 0, s[92:93]
	s_mov_b32 m0, s10
	ds_read_b128 v[192:195], v151 offset:49152
	ds_read_b128 v[196:199], v151 offset:50176
	ds_read_b128 v[200:203], v151 offset:51200
	ds_read_b128 v[204:207], v151 offset:52224
	ds_read_b128 v[208:211], v151 offset:53248
	ds_read_b128 v[212:215], v151 offset:54272
	ds_read_b128 v[216:219], v151 offset:55296
	ds_read_b128 v[240:243], v151 offset:56320
	global_load_lds_dwordx4 v[146:147], off
	v_lshl_add_u64 v[146:147], v[246:247], 0, s[92:93]
	s_add_i32 m0, s10, 0x2000
	s_add_i32 s10, s62, s45
	global_load_lds_dwordx4 v[146:147], off
	v_lshl_add_u64 v[146:147], v[248:249], 0, s[92:93]
	s_mov_b32 m0, s10
	s_nop 0
	global_load_lds_dwordx4 v[146:147], off
	v_lshl_add_u64 v[146:147], v[220:221], 0, s[92:93]
	s_add_i32 m0, s10, 0x2000
	s_nop 0
	global_load_lds_dwordx4 v[146:147], off
	v_lshl_add_u64 v[146:147], v[250:251], 0, s[92:93]
	s_mov_b32 m0, s53
	s_nop 0
	global_load_lds_dwordx4 v[146:147], off
	v_lshl_add_u64 v[146:147], v[252:253], 0, s[92:93]
	s_mov_b32 m0, s54
	s_nop 0
	global_load_lds_dwordx4 v[146:147], off
	s_waitcnt vmcnt(8)
	s_waitcnt lgkmcnt(0)
	s_barrier
	s_setprio 1
	s_waitcnt lgkmcnt(0)
	v_mfma_f32_16x16x32_bf16 v[60:63], v[152:155], v[192:195], v[60:63]
	v_mfma_f32_16x16x32_bf16 v[56:59], v[160:163], v[192:195], v[56:59]
	v_mfma_f32_16x16x32_bf16 v[44:47], v[152:155], v[200:203], v[44:47]
	v_mfma_f32_16x16x32_bf16 v[40:43], v[160:163], v[200:203], v[40:43]
	v_mfma_f32_16x16x32_bf16 v[28:31], v[152:155], v[208:211], v[28:31]
	v_mfma_f32_16x16x32_bf16 v[24:27], v[160:163], v[208:211], v[24:27]
	v_mfma_f32_16x16x32_bf16 v[12:15], v[152:155], v[216:219], v[12:15]
	v_mfma_f32_16x16x32_bf16 v[8:11], v[160:163], v[216:219], v[8:11]
	v_mfma_f32_16x16x32_bf16 v[60:63], v[156:159], v[196:199], v[60:63]
	v_mfma_f32_16x16x32_bf16 v[56:59], v[164:167], v[196:199], v[56:59]
	v_mfma_f32_16x16x32_bf16 v[44:47], v[156:159], v[204:207], v[44:47]
	v_mfma_f32_16x16x32_bf16 v[40:43], v[164:167], v[204:207], v[40:43]
	v_mfma_f32_16x16x32_bf16 v[28:31], v[156:159], v[212:215], v[28:31]
	v_mfma_f32_16x16x32_bf16 v[24:27], v[164:167], v[212:215], v[24:27]
	v_mfma_f32_16x16x32_bf16 v[12:15], v[156:159], v[240:243], v[12:15]
	v_mfma_f32_16x16x32_bf16 v[8:11], v[164:167], v[240:243], v[8:11]
	s_setprio 0
	s_setprio 1
	v_mfma_f32_16x16x32_bf16 v[52:55], v[176:179], v[192:195], v[52:55]
	v_mfma_f32_16x16x32_bf16 v[48:51], v[184:187], v[192:195], v[48:51]
	v_mfma_f32_16x16x32_bf16 v[36:39], v[176:179], v[200:203], v[36:39]
	v_mfma_f32_16x16x32_bf16 v[32:35], v[184:187], v[200:203], v[32:35]
	v_mfma_f32_16x16x32_bf16 v[20:23], v[176:179], v[208:211], v[20:23]
	v_mfma_f32_16x16x32_bf16 v[16:19], v[184:187], v[208:211], v[16:19]
	v_mfma_f32_16x16x32_bf16 v[4:7], v[176:179], v[216:219], v[4:7]
	v_mfma_f32_16x16x32_bf16 v[0:3], v[184:187], v[216:219], v[0:3]
	v_mfma_f32_16x16x32_bf16 v[52:55], v[180:183], v[196:199], v[52:55]
	v_mfma_f32_16x16x32_bf16 v[48:51], v[188:191], v[196:199], v[48:51]
	v_mfma_f32_16x16x32_bf16 v[36:39], v[180:183], v[204:207], v[36:39]
	v_mfma_f32_16x16x32_bf16 v[32:35], v[188:191], v[204:207], v[32:35]
	v_mfma_f32_16x16x32_bf16 v[20:23], v[180:183], v[212:215], v[20:23]
	v_mfma_f32_16x16x32_bf16 v[16:19], v[188:191], v[212:215], v[16:19]
	v_mfma_f32_16x16x32_bf16 v[4:7], v[180:183], v[240:243], v[4:7]
	v_mfma_f32_16x16x32_bf16 v[0:3], v[188:191], v[240:243], v[0:3]
	s_setprio 0
	s_barrier
	v_lshl_add_u64 v[142:143], v[142:143], 0, s[80:81]
	v_lshl_add_u64 v[144:145], v[144:145], 0, s[80:81]
	s_mov_b32 s10, s11
	s_cmp_lg_u32 s10, s55
	s_cbranch_scc1 .LBB0_354
; #define PG8_STAGE(bufoff, gbase, voff) do { _Pragma("unroll") for (int _i = 0; _i < 2; ++_i) \
;         __builtin_amdgcn_global_load_lds((const unsigned*)((const char*)(gbase) + (voff)[_i]), (LAS unsigned*)(lds + (bufoff) + ldsw + _i * 8192), 16, 0, 0); } while (0)
; #define PG8_LDA(dst, b, h) do { _Pragma("unroll") for (int m = 0; m < 4; ++m) _Pragma("unroll") for (int k = 0; k < 2; ++k) dst[m][k] = *(const LAS bf16x8*)(lds + PG8_SA(b, h) + aoff + m * 2048 + k * 1024); } while (0)
; #define PG8_LDB(dst, b, h) do { _Pragma("unroll") for (int n = 0; n < 2; ++n) _Pragma("unroll") for (int k = 0; k < 2; ++k) dst[n][k] = *(const LAS bf16x8*)(lds + PG8_SB(b, h) + boff + n * 2048 + k * 1024); } while (0)
; #define PG8_MMA(ai, bj, At, Bt) do { __builtin_amdgcn_s_setprio(1); _Pragma("unroll") for (int k = 0; k < 2; ++k) _Pragma("unroll") for (int m = 0; m < 4; ++m) _Pragma("unroll") for (int n = 0; n < 2; ++n) \
;         acc[ai][bj][m][n] = __builtin_amdgcn_mfma_f32_16x16x32_bf16(Bt[n][k], At[m][k], acc[ai][bj][m][n], 0, 0, 0); __builtin_amdgcn_s_setprio(0); } while (0)
; #define PG8_WAIT_V(n) asm volatile("s_waitcnt vmcnt(" #n ")" ::: "memory")
; #define PG8_WAIT_L(n) asm volatile("s_waitcnt lgkmcnt(" #n ")" ::: "memory")
; #define PG8_BAR __builtin_amdgcn_s_barrier()
; #define PG8_SCHED __builtin_amdgcn_sched_barrier(0)
; template <class Epi, bool ALIGN_EPI>
; __device__ __forceinline__ void gemm_phase(LAS unsigned char* lds, const Gemm g, const StaticOrder& S, const Epi& E, const int tid) {
;     ...
;             PG8_LDB(B0, 0, 0); PG8_LDB(B1, 0, 1); PG8_SCHED; PG8_LDA(At, 0, 0); PG8_STAGE(PG8_SA(1, 1), a1 + hA, voffA);
;             PG8_WAIT_V(8); PG8_WAIT_L(0); PG8_BAR; PG8_MMA(0, 0, At, B0); PG8_MMA(0, 1, At, B1); PG8_BAR; PG8_SCHED;
;             PG8_LDA(At, 0, 1); PG8_STAGE(PG8_SB(0, 0), b2, voffB); PG8_STAGE(PG8_SB(0, 1), b2 + hB, voffB); PG8_STAGE(PG8_SA(0, 0), a2, voffA);
;             PG8_WAIT_V(8); PG8_WAIT_L(0); PG8_BAR; PG8_MMA(1, 0, At, B0); PG8_MMA(1, 1, At, B1); PG8_BAR; PG8_SCHED;
.Lq5_last:
	s_add_i32 s11, s10, 2
	s_cmp_eq_u32 s55, s10
	s_cselect_b64 vcc, -1, 0
	v_add_u32_e32 v148, s33, v149
	s_add_i32 s10, 0, 0x14000
	ds_read_b128 v[152:155], v148
	ds_read_b128 v[156:159], v148 offset:1024
	ds_read_b128 v[160:163], v148 offset:2048
	ds_read_b128 v[164:167], v148 offset:3072
	v_add_u32_e32 v148, s10, v149
	ds_read_b128 v[176:179], v148
	ds_read_b128 v[180:183], v148 offset:1024
	ds_read_b128 v[184:187], v148 offset:2048
	ds_read_b128 v[188:191], v148 offset:3072
	v_lshl_add_u64 v[146:147], v[142:143], 0, s[92:93]
	v_cndmask_b32_e32 v147, v147, v139, vcc
	v_cndmask_b32_e32 v146, v146, v138, vcc
	v_cndmask_b32_e32 v221, v145, v141, vcc
	v_cndmask_b32_e32 v220, v144, v140, vcc
	v_lshl_add_u64 v[244:245], v[142:143], 0, v[134:135]
	s_add_i32 m0, s25, 0xc000
	ds_read_b128 v[192:195], v151
	ds_read_b128 v[196:199], v151 offset:1024
	ds_read_b128 v[200:203], v151 offset:2048
	ds_read_b128 v[204:207], v151 offset:3072
	ds_read_b128 v[208:211], v151 offset:4096
	ds_read_b128 v[212:215], v151 offset:5120
	ds_read_b128 v[216:219], v151 offset:6144
	ds_read_b128 v[240:243], v151 offset:7168
	global_load_lds_dwordx4 v[244:245], off
	v_lshl_add_u64 v[244:245], v[142:143], 0, v[136:137]
	s_add_i32 m0, s25, 0xe000
	s_nop 0
	global_load_lds_dwordx4 v[244:245], off
	s_waitcnt vmcnt(8)
	s_waitcnt lgkmcnt(0)
	s_barrier
	s_setprio 1
	s_waitcnt lgkmcnt(0)
	v_mfma_f32_16x16x32_bf16 v[124:127], v[152:155], v[192:195], v[124:127]
	v_mfma_f32_16x16x32_bf16 v[120:123], v[160:163], v[192:195], v[120:123]
	v_mfma_f32_16x16x32_bf16 v[108:111], v[152:155], v[200:203], v[108:111]
	v_mfma_f32_16x16x32_bf16 v[104:107], v[160:163], v[200:203], v[104:107]
	v_mfma_f32_16x16x32_bf16 v[92:95], v[152:155], v[208:211], v[92:95]
	v_mfma_f32_16x16x32_bf16 v[88:91], v[160:163], v[208:211], v[88:91]
	v_mfma_f32_16x16x32_bf16 v[76:79], v[152:155], v[216:219], v[76:79]
	v_mfma_f32_16x16x32_bf16 v[72:75], v[160:163], v[216:219], v[72:75]
	v_mfma_f32_16x16x32_bf16 v[124:127], v[156:159], v[196:199], v[124:127]
	v_mfma_f32_16x16x32_bf16 v[120:123], v[164:167], v[196:199], v[120:123]
	v_mfma_f32_16x16x32_bf16 v[108:111], v[156:159], v[204:207], v[108:111]
	v_mfma_f32_16x16x32_bf16 v[104:107], v[164:167], v[204:207], v[104:107]
	v_mfma_f32_16x16x32_bf16 v[92:95], v[156:159], v[212:215], v[92:95]
	v_mfma_f32_16x16x32_bf16 v[88:91], v[164:167], v[212:215], v[88:91]
	v_mfma_f32_16x16x32_bf16 v[76:79], v[156:159], v[240:243], v[76:79]
	v_mfma_f32_16x16x32_bf16 v[72:75], v[164:167], v[240:243], v[72:75]
	s_setprio 0
	s_setprio 1
	v_mfma_f32_16x16x32_bf16 v[116:119], v[176:179], v[192:195], v[116:119]
	v_mfma_f32_16x16x32_bf16 v[112:115], v[184:187], v[192:195], v[112:115]
	v_mfma_f32_16x16x32_bf16 v[100:103], v[176:179], v[200:203], v[100:103]
	v_mfma_f32_16x16x32_bf16 v[96:99], v[184:187], v[200:203], v[96:99]
	v_mfma_f32_16x16x32_bf16 v[84:87], v[176:179], v[208:211], v[84:87]
	v_mfma_f32_16x16x32_bf16 v[80:83], v[184:187], v[208:211], v[80:83]
	v_mfma_f32_16x16x32_bf16 v[68:71], v[176:179], v[216:219], v[68:71]
	v_mfma_f32_16x16x32_bf16 v[64:67], v[184:187], v[216:219], v[64:67]
	v_mfma_f32_16x16x32_bf16 v[116:119], v[180:183], v[196:199], v[116:119]
	v_mfma_f32_16x16x32_bf16 v[112:115], v[188:191], v[196:199], v[112:115]
	v_mfma_f32_16x16x32_bf16 v[100:103], v[180:183], v[204:207], v[100:103]
	v_mfma_f32_16x16x32_bf16 v[96:99], v[188:191], v[204:207], v[96:99]
	v_mfma_f32_16x16x32_bf16 v[84:87], v[180:183], v[212:215], v[84:87]
	v_mfma_f32_16x16x32_bf16 v[80:83], v[188:191], v[212:215], v[80:83]
	v_mfma_f32_16x16x32_bf16 v[68:71], v[180:183], v[240:243], v[68:71]
	v_mfma_f32_16x16x32_bf16 v[64:67], v[188:191], v[240:243], v[64:67]
	s_setprio 0
	s_barrier
	s_add_i32 s62, s33, s45
	v_lshl_add_u64 v[244:245], v[220:221], 0, v[168:169]
	s_mov_b32 m0, s62
	ds_read_b128 v[192:195], v151 offset:16384
	ds_read_b128 v[196:199], v151 offset:17408
	ds_read_b128 v[200:203], v151 offset:18432
	ds_read_b128 v[204:207], v151 offset:19456
	ds_read_b128 v[208:211], v151 offset:20480
	ds_read_b128 v[212:215], v151 offset:21504
	ds_read_b128 v[216:219], v151 offset:22528
	ds_read_b128 v[240:243], v151 offset:23552
	global_load_lds_dwordx4 v[244:245], off
	v_lshl_add_u64 v[246:247], v[220:221], 0, v[128:129]
	s_add_i32 m0, s62, 0x2000
	v_lshl_add_u64 v[220:221], v[220:221], 0, s[12:13]
	s_add_i32 s10, s10, s45
	global_load_lds_dwordx4 v[246:247], off
	v_lshl_add_u64 v[248:249], v[220:221], 0, v[168:169]
	s_mov_b32 m0, s10
	v_lshl_add_u64 v[220:221], v[220:221], 0, v[128:129]
	global_load_lds_dwordx4 v[248:249], off
	s_add_i32 m0, s10, 0x2000
	v_lshl_add_u64 v[250:251], v[146:147], 0, v[132:133]
	global_load_lds_dwordx4 v[220:221], off
	s_mov_b32 m0, s25
	v_lshl_add_u64 v[252:253], v[146:147], 0, v[130:131]
	global_load_lds_dwordx4 v[250:251], off
	s_mov_b32 m0, s50
	s_nop 0
	global_load_lds_dwordx4 v[252:253], off
	s_waitcnt vmcnt(8)
	s_waitcnt lgkmcnt(0)
	s_barrier
; #define PG8_STAGE(bufoff, gbase, voff) do { _Pragma("unroll") for (int _i = 0; _i < 2; ++_i) \
;         __builtin_amdgcn_global_load_lds((const unsigned*)((const char*)(gbase) + (voff)[_i]), (LAS unsigned*)(lds + (bufoff) + ldsw + _i * 8192), 16, 0, 0); } while (0)
; #define PG8_LDA(dst, b, h) do { _Pragma("unroll") for (int m = 0; m < 4; ++m) _Pragma("unroll") for (int k = 0; k < 2; ++k) dst[m][k] = *(const LAS bf16x8*)(lds + PG8_SA(b, h) + aoff + m * 2048 + k * 1024); } while (0)
; #define PG8_LDB(dst, b, h) do { _Pragma("unroll") for (int n = 0; n < 2; ++n) _Pragma("unroll") for (int k = 0; k < 2; ++k) dst[n][k] = *(const LAS bf16x8*)(lds + PG8_SB(b, h) + boff + n * 2048 + k * 1024); } while (0)
; #define PG8_MMA(ai, bj, At, Bt) do { __builtin_amdgcn_s_setprio(1); _Pragma("unroll") for (int k = 0; k < 2; ++k) _Pragma("unroll") for (int m = 0; m < 4; ++m) _Pragma("unroll") for (int n = 0; n < 2; ++n) \
;         acc[ai][bj][m][n] = __builtin_amdgcn_mfma_f32_16x16x32_bf16(Bt[n][k], At[m][k], acc[ai][bj][m][n], 0, 0, 0); __builtin_amdgcn_s_setprio(0); } while (0)
; #define PG8_WAIT_V(n) asm volatile("s_waitcnt vmcnt(" #n ")" ::: "memory")
; #define PG8_WAIT_L(n) asm volatile("s_waitcnt lgkmcnt(" #n ")" ::: "memory")
; #define PG8_BAR __builtin_amdgcn_s_barrier()
; #define PG8_SCHED __builtin_amdgcn_sched_barrier(0)
; template <class Epi, bool ALIGN_EPI>
; __device__ __forceinline__ void gemm_phase(LAS unsigned char* lds, const Gemm g, const StaticOrder& S, const Epi& E, const int tid) {
;     ...
;             PG8_WAIT_V(8); PG8_WAIT_L(0); PG8_BAR; PG8_MMA(1, 0, At, B0); PG8_MMA(1, 1, At, B1); PG8_BAR; PG8_SCHED;
;             PG8_LDB(B0, 1, 0); PG8_LDB(B1, 1, 1); PG8_SCHED; PG8_LDA(At, 1, 0); PG8_STAGE(PG8_SA(0, 1), a2 + hA, voffA);
;             PG8_WAIT_V(8); PG8_WAIT_L(0); PG8_BAR; PG8_MMA(0, 0, At, B0); PG8_MMA(0, 1, At, B1); PG8_BAR; PG8_SCHED;
;             PG8_LDA(At, 1, 1); PG8_STAGE(PG8_SB(1, 0), b3, voffB); PG8_STAGE(PG8_SB(1, 1), b3 + hB, voffB); PG8_STAGE(PG8_SA(1, 0), a3, voffA);
	s_setprio 1
	s_waitcnt lgkmcnt(0)
	v_mfma_f32_16x16x32_bf16 v[60:63], v[152:155], v[192:195], v[60:63]
	v_mfma_f32_16x16x32_bf16 v[56:59], v[160:163], v[192:195], v[56:59]
	v_mfma_f32_16x16x32_bf16 v[44:47], v[152:155], v[200:203], v[44:47]
	v_mfma_f32_16x16x32_bf16 v[40:43], v[160:163], v[200:203], v[40:43]
	v_mfma_f32_16x16x32_bf16 v[28:31], v[152:155], v[208:211], v[28:31]
	v_mfma_f32_16x16x32_bf16 v[24:27], v[160:163], v[208:211], v[24:27]
	v_mfma_f32_16x16x32_bf16 v[12:15], v[152:155], v[216:219], v[12:15]
	v_mfma_f32_16x16x32_bf16 v[8:11], v[160:163], v[216:219], v[8:11]
	v_mfma_f32_16x16x32_bf16 v[60:63], v[156:159], v[196:199], v[60:63]
	v_mfma_f32_16x16x32_bf16 v[56:59], v[164:167], v[196:199], v[56:59]
	v_mfma_f32_16x16x32_bf16 v[44:47], v[156:159], v[204:207], v[44:47]
	v_mfma_f32_16x16x32_bf16 v[40:43], v[164:167], v[204:207], v[40:43]
	v_mfma_f32_16x16x32_bf16 v[28:31], v[156:159], v[212:215], v[28:31]
	v_mfma_f32_16x16x32_bf16 v[24:27], v[164:167], v[212:215], v[24:27]
	v_mfma_f32_16x16x32_bf16 v[12:15], v[156:159], v[240:243], v[12:15]
	v_mfma_f32_16x16x32_bf16 v[8:11], v[164:167], v[240:243], v[8:11]
	s_setprio 0
	s_setprio 1
	v_mfma_f32_16x16x32_bf16 v[52:55], v[176:179], v[192:195], v[52:55]
	v_mfma_f32_16x16x32_bf16 v[48:51], v[184:187], v[192:195], v[48:51]
	v_mfma_f32_16x16x32_bf16 v[36:39], v[176:179], v[200:203], v[36:39]
	v_mfma_f32_16x16x32_bf16 v[32:35], v[184:187], v[200:203], v[32:35]
	v_mfma_f32_16x16x32_bf16 v[20:23], v[176:179], v[208:211], v[20:23]
	v_mfma_f32_16x16x32_bf16 v[16:19], v[184:187], v[208:211], v[16:19]
	v_mfma_f32_16x16x32_bf16 v[4:7], v[176:179], v[216:219], v[4:7]
	v_mfma_f32_16x16x32_bf16 v[0:3], v[184:187], v[216:219], v[0:3]
	v_mfma_f32_16x16x32_bf16 v[52:55], v[180:183], v[196:199], v[52:55]
	v_mfma_f32_16x16x32_bf16 v[48:51], v[188:191], v[196:199], v[48:51]
	v_mfma_f32_16x16x32_bf16 v[36:39], v[180:183], v[204:207], v[36:39]
	v_mfma_f32_16x16x32_bf16 v[32:35], v[188:191], v[204:207], v[32:35]
	v_mfma_f32_16x16x32_bf16 v[20:23], v[180:183], v[212:215], v[20:23]
	v_mfma_f32_16x16x32_bf16 v[16:19], v[188:191], v[212:215], v[16:19]
	v_mfma_f32_16x16x32_bf16 v[4:7], v[180:183], v[240:243], v[4:7]
	v_mfma_f32_16x16x32_bf16 v[0:3], v[188:191], v[240:243], v[0:3]
	s_setprio 0
	s_barrier
	s_add_i32 s10, 0, 0x18000
	v_add_u32_e32 v148, s10, v149
	s_add_i32 s62, 0, 0x1c000
	ds_read_b128 v[152:155], v148
	ds_read_b128 v[156:159], v148 offset:1024
	ds_read_b128 v[160:163], v148 offset:2048
	ds_read_b128 v[164:167], v148 offset:3072
	v_add_u32_e32 v148, s62, v149
	ds_read_b128 v[176:179], v148
	ds_read_b128 v[180:183], v148 offset:1024
	ds_read_b128 v[184:187], v148 offset:2048
	ds_read_b128 v[188:191], v148 offset:3072
	v_lshl_add_u64 v[146:147], v[146:147], 0, s[94:95]
	s_mov_b32 m0, s51
	v_lshl_add_u64 v[226:227], v[146:147], 0, v[132:133]
	ds_read_b128 v[192:195], v151 offset:32768
	ds_read_b128 v[196:199], v151 offset:33792
	ds_read_b128 v[200:203], v151 offset:34816
	ds_read_b128 v[204:207], v151 offset:35840
	ds_read_b128 v[208:211], v151 offset:36864
	ds_read_b128 v[212:215], v151 offset:37888
	ds_read_b128 v[216:219], v151 offset:38912
	ds_read_b128 v[240:243], v151 offset:39936
	global_load_lds_dwordx4 v[226:227], off
	v_lshl_add_u64 v[146:147], v[146:147], 0, v[130:131]
	s_mov_b32 m0, s52
	s_nop 0
	global_load_lds_dwordx4 v[146:147], off
	s_waitcnt vmcnt(8)
	s_waitcnt lgkmcnt(0)
	s_barrier
	s_setprio 1
	s_waitcnt lgkmcnt(0)
	v_mfma_f32_16x16x32_bf16 v[124:127], v[152:155], v[192:195], v[124:127]
	v_mfma_f32_16x16x32_bf16 v[120:123], v[160:163], v[192:195], v[120:123]
	v_mfma_f32_16x16x32_bf16 v[108:111], v[152:155], v[200:203], v[108:111]
	v_mfma_f32_16x16x32_bf16 v[104:107], v[160:163], v[200:203], v[104:107]
	v_mfma_f32_16x16x32_bf16 v[92:95], v[152:155], v[208:211], v[92:95]
	v_mfma_f32_16x16x32_bf16 v[88:91], v[160:163], v[208:211], v[88:91]
	v_mfma_f32_16x16x32_bf16 v[76:79], v[152:155], v[216:219], v[76:79]
	v_mfma_f32_16x16x32_bf16 v[72:75], v[160:163], v[216:219], v[72:75]
	v_mfma_f32_16x16x32_bf16 v[124:127], v[156:159], v[196:199], v[124:127]
	v_mfma_f32_16x16x32_bf16 v[120:123], v[164:167], v[196:199], v[120:123]
	v_mfma_f32_16x16x32_bf16 v[108:111], v[156:159], v[204:207], v[108:111]
	v_mfma_f32_16x16x32_bf16 v[104:107], v[164:167], v[204:207], v[104:107]
	v_mfma_f32_16x16x32_bf16 v[92:95], v[156:159], v[212:215], v[92:95]
	v_mfma_f32_16x16x32_bf16 v[88:91], v[164:167], v[212:215], v[88:91]
	v_mfma_f32_16x16x32_bf16 v[76:79], v[156:159], v[240:243], v[76:79]
	v_mfma_f32_16x16x32_bf16 v[72:75], v[164:167], v[240:243], v[72:75]
	s_setprio 0
	s_setprio 1
	v_mfma_f32_16x16x32_bf16 v[116:119], v[176:179], v[192:195], v[116:119]
	v_mfma_f32_16x16x32_bf16 v[112:115], v[184:187], v[192:195], v[112:115]
	v_mfma_f32_16x16x32_bf16 v[100:103], v[176:179], v[200:203], v[100:103]
	v_mfma_f32_16x16x32_bf16 v[96:99], v[184:187], v[200:203], v[96:99]
	v_mfma_f32_16x16x32_bf16 v[84:87], v[176:179], v[208:211], v[84:87]
	v_mfma_f32_16x16x32_bf16 v[80:83], v[184:187], v[208:211], v[80:83]
	v_mfma_f32_16x16x32_bf16 v[68:71], v[176:179], v[216:219], v[68:71]
	v_mfma_f32_16x16x32_bf16 v[64:67], v[184:187], v[216:219], v[64:67]
	v_mfma_f32_16x16x32_bf16 v[116:119], v[180:183], v[196:199], v[116:119]
	v_mfma_f32_16x16x32_bf16 v[112:115], v[188:191], v[196:199], v[112:115]
	v_mfma_f32_16x16x32_bf16 v[100:103], v[180:183], v[204:207], v[100:103]
	v_mfma_f32_16x16x32_bf16 v[96:99], v[188:191], v[204:207], v[96:99]
	v_mfma_f32_16x16x32_bf16 v[84:87], v[180:183], v[212:215], v[84:87]
	v_mfma_f32_16x16x32_bf16 v[80:83], v[188:191], v[212:215], v[80:83]
	v_mfma_f32_16x16x32_bf16 v[68:71], v[180:183], v[240:243], v[68:71]
	v_mfma_f32_16x16x32_bf16 v[64:67], v[188:191], v[240:243], v[64:67]
	s_setprio 0
	s_barrier
; #define PG8_STAGE(bufoff, gbase, voff) do { _Pragma("unroll") for (int _i = 0; _i < 2; ++_i) \
;         __builtin_amdgcn_global_load_lds((const unsigned*)((const char*)(gbase) + (voff)[_i]), (LAS unsigned*)(lds + (bufoff) + ldsw + _i * 8192), 16, 0, 0); } while (0)
; #define PG8_LDA(dst, b, h) do { _Pragma("unroll") for (int m = 0; m < 4; ++m) _Pragma("unroll") for (int k = 0; k < 2; ++k) dst[m][k] = *(const LAS bf16x8*)(lds + PG8_SA(b, h) + aoff + m * 2048 + k * 1024); } while (0)
; template <class Epi, bool ALIGN_EPI>
; __device__ __forceinline__ void gemm_phase(LAS unsigned char* lds, const Gemm g, const StaticOrder& S, const Epi& E, const int tid) {
;     ...
;             PG8_LDA(At, 1, 1); PG8_STAGE(PG8_SB(1, 0), b3, voffB); PG8_STAGE(PG8_SB(1, 1), b3 + hB, voffB); PG8_STAGE(PG8_SA(1, 0), a3, voffA);
	s_add_i32 s10, s10, s45
	v_lshl_add_u64 v[146:147], v[244:245], 0, s[92:93]
	s_mov_b32 m0, s10
	ds_read_b128 v[192:195], v151 offset:49152
	ds_read_b128 v[196:199], v151 offset:50176
	ds_read_b128 v[200:203], v151 offset:51200
	ds_read_b128 v[204:207], v151 offset:52224
	ds_read_b128 v[208:211], v151 offset:53248
	ds_read_b128 v[212:215], v151 offset:54272
	ds_read_b128 v[216:219], v151 offset:55296
	ds_read_b128 v[240:243], v151 offset:56320
	global_load_lds_dwordx4 v[146:147], off
	v_lshl_add_u64 v[146:147], v[246:247], 0, s[92:93]
	s_add_i32 m0, s10, 0x2000
	s_add_i32 s10, s62, s45
	global_load_lds_dwordx4 v[146:147], off
	v_lshl_add_u64 v[146:147], v[248:249], 0, s[92:93]
	s_mov_b32 m0, s10
	s_nop 0
	global_load_lds_dwordx4 v[146:147], off
	v_lshl_add_u64 v[146:147], v[220:221], 0, s[92:93]
	s_add_i32 m0, s10, 0x2000
	s_nop 0
	global_load_lds_dwordx4 v[146:147], off
	v_lshl_add_u64 v[146:147], v[250:251], 0, s[92:93]
	s_mov_b32 m0, s53
	s_nop 0
	global_load_lds_dwordx4 v[146:147], off
	v_lshl_add_u64 v[146:147], v[252:253], 0, s[92:93]
	s_mov_b32 m0, s54
	s_nop 0
	global_load_lds_dwordx4 v[146:147], off
	s_waitcnt vmcnt(8)
	s_waitcnt lgkmcnt(0)
	s_barrier
; __device__ __forceinline__ unsigned cvt_pk_bf16(float lo, float hi) { unsigned r; asm volatile("v_cvt_pk_bf16_f32 %0, %1, %2" : "=v"(r) : "v"(lo), "v"(hi)); return r; }
; __device__ __forceinline__ float gelu_tanh(float x) { const float u = 0.7978845608028654f * (x + 0.044715f * x * x * x); return x * fast_rcp(1.0f + fast_exp2(-2.0f * LOG2E * u)); }
; #define PG8_MMA(ai, bj, At, Bt) do { __builtin_amdgcn_s_setprio(1); _Pragma("unroll") for (int k = 0; k < 2; ++k) _Pragma("unroll") for (int m = 0; m < 4; ++m) _Pragma("unroll") for (int n = 0; n < 2; ++n) \
;         acc[ai][bj][m][n] = __builtin_amdgcn_mfma_f32_16x16x32_bf16(Bt[n][k], At[m][k], acc[ai][bj][m][n], 0, 0, 0); __builtin_amdgcn_s_setprio(0); } while (0)
; #define PG8_WAIT_V(n) asm volatile("s_waitcnt vmcnt(" #n ")" ::: "memory")
; #define PG8_WAIT_L(n) asm volatile("s_waitcnt lgkmcnt(" #n ")" ::: "memory")
; #define PG8_BAR __builtin_amdgcn_s_barrier()
; #define PG8_SCHED __builtin_amdgcn_sched_barrier(0)
;     __device__ __forceinline__ void operator()(const f32x4 (&acc)[2][2][4][2], const Unit& u, int wr, int wc, int fr, int fq) const {
;         const int row0 = u.pm * BM + wr * 64 + fr, col0 = u.pn * BM + wc * 32 + 8 * fq;
;         float rsv[2][4]; load_rstd(rsv, ssq, row0);
; #pragma unroll
;         for (int ai = 0; ai < 2; ++ai)
; #pragma unroll
;             for (int m = 0; m < 4; ++m) { const int row = row0 + ai * HALF + m * 16; bf16_t* rowp = O + (size_t)row * ldc + col0; const float rs = rsv[ai][m];
; #pragma unroll
;                 for (int bj = 0; bj < 2; ++bj) { f32x4 v0 = acc[ai][bj][m][0] * rs, v1 = acc[ai][bj][m][1] * rs;
;                     if (ACT == 1) {
; #pragma unroll
;                         for (int j = 0; j < 4; ++j) { v0[j] = gelu_tanh(v0[j]); v1[j] = gelu_tanh(v1[j]); } }
;                     u32x4 w; w.x = cvt_pk_bf16(v0[0], v0[1]); w.y = cvt_pk_bf16(v0[2], v0[3]); w.z = cvt_pk_bf16(v1[0], v1[1]); w.w = cvt_pk_bf16(v1[2], v1[3]);
;                     *(u32x4*)(rowp + bj * HALF) = w; } }
; template <class Epi, bool ALIGN_EPI>
; __device__ __forceinline__ void gemm_phase(LAS unsigned char* lds, const Gemm g, const StaticOrder& S, const Epi& E, const int tid) {
;     ...
;             PG8_WAIT_V(8); PG8_WAIT_L(0); PG8_BAR; PG8_MMA(1, 0, At, B0); PG8_MMA(1, 1, At, B1); PG8_BAR; PG8_SCHED;
	s_setprio 1
	s_waitcnt lgkmcnt(0)
	v_mfma_f32_16x16x32_bf16 v[60:63], v[152:155], v[192:195], v[60:63]
	v_lshrrev_b32_e32 v171, 8, v170
	v_and_b32_e32 v234, 15, v170
	v_lshl_add_u32 v171, v171, 6, v234
	s_lshl_b32 s98, s61, 8
	v_add_u32_e32 v171, s98, v171
	v_mfma_f32_16x16x32_bf16 v[56:59], v[160:163], v[192:195], v[56:59]
	v_mul_lo_u32 v171, v171, s28
	v_bfe_u32 v234, v170, 6, 2
	v_bfe_u32 v224, v170, 4, 2
	v_lshlrev_b32_e32 v234, 5, v234
	v_lshl_or_b32 v234, v224, 3, v234
	v_mfma_f32_16x16x32_bf16 v[44:47], v[152:155], v[200:203], v[44:47]
	s_lshl_b32 s98, s60, 8
	v_add_u32_e32 v234, s98, v234
	v_add_lshl_u32 v232, v171, v234, 1
	v_mov_b32_e32 v233, 0
	v_lshl_add_u64 v[232:233], v[232:233], 0, s[30:31]
	v_mfma_f32_16x16x32_bf16 v[40:43], v[160:163], v[200:203], v[40:43]
	s_lshl_b32 s98, s28, 5
	s_mov_b32 s99, 0
	v_mul_f32_e32 v124, v172, v124
	v_mul_f32_e32 v125, v172, v125
	v_mul_f32_e32 v126, v172, v126
	v_mfma_f32_16x16x32_bf16 v[28:31], v[152:155], v[208:211], v[28:31]
	v_mul_f32_e32 v127, v172, v127
	v_mul_f32_e32 v120, v172, v120
	v_mul_f32_e32 v121, v172, v121
	v_mul_f32_e32 v122, v172, v122
	v_mul_f32_e32 v123, v172, v123
	v_mfma_f32_16x16x32_bf16 v[24:27], v[160:163], v[208:211], v[24:27]
	v_cvt_pk_bf16_f32 v124, v124, v125
	v_cvt_pk_bf16_f32 v125, v126, v127
	v_cvt_pk_bf16_f32 v126, v120, v121
	v_cvt_pk_bf16_f32 v127, v122, v123
	global_store_dwordx4 v[232:233], v[124:127], off
	v_mfma_f32_16x16x32_bf16 v[12:15], v[152:155], v[216:219], v[12:15]
	v_mul_f32_e32 v116, v172, v116
	v_mul_f32_e32 v117, v172, v117
	v_mul_f32_e32 v118, v172, v118
	v_mul_f32_e32 v119, v172, v119
	v_mul_f32_e32 v112, v172, v112
	v_mfma_f32_16x16x32_bf16 v[8:11], v[160:163], v[216:219], v[8:11]
	v_mul_f32_e32 v113, v172, v113
	v_mul_f32_e32 v114, v172, v114
	v_mul_f32_e32 v115, v172, v115
	v_cvt_pk_bf16_f32 v116, v116, v117
	v_cvt_pk_bf16_f32 v117, v118, v119
	v_mfma_f32_16x16x32_bf16 v[60:63], v[156:159], v[196:199], v[60:63]
	v_cvt_pk_bf16_f32 v118, v112, v113
	v_cvt_pk_bf16_f32 v119, v114, v115
	global_store_dwordx4 v[232:233], v[116:119], off offset:256
	v_lshl_add_u64 v[232:233], v[232:233], 0, s[98:99]
	v_mul_f32_e32 v108, v173, v108
	v_mfma_f32_16x16x32_bf16 v[56:59], v[164:167], v[196:199], v[56:59]
	v_mul_f32_e32 v109, v173, v109
	v_mul_f32_e32 v110, v173, v110
	v_mul_f32_e32 v111, v173, v111
	v_mul_f32_e32 v104, v173, v104
	v_mul_f32_e32 v105, v173, v105
	v_mfma_f32_16x16x32_bf16 v[44:47], v[156:159], v[204:207], v[44:47]
	v_mul_f32_e32 v106, v173, v106
	v_mul_f32_e32 v107, v173, v107
	v_cvt_pk_bf16_f32 v108, v108, v109
	v_cvt_pk_bf16_f32 v109, v110, v111
	v_cvt_pk_bf16_f32 v110, v104, v105
	v_mfma_f32_16x16x32_bf16 v[40:43], v[164:167], v[204:207], v[40:43]
	v_cvt_pk_bf16_f32 v111, v106, v107
	global_store_dwordx4 v[232:233], v[108:111], off
	v_mul_f32_e32 v100, v173, v100
	v_mul_f32_e32 v101, v173, v101
	v_mul_f32_e32 v102, v173, v102
	v_mfma_f32_16x16x32_bf16 v[28:31], v[156:159], v[212:215], v[28:31]
	v_mul_f32_e32 v103, v173, v103
	v_mul_f32_e32 v96, v173, v96
	v_mul_f32_e32 v97, v173, v97
	v_mul_f32_e32 v98, v173, v98
	v_mul_f32_e32 v99, v173, v99
	v_mfma_f32_16x16x32_bf16 v[24:27], v[164:167], v[212:215], v[24:27]
	v_cvt_pk_bf16_f32 v100, v100, v101
	v_cvt_pk_bf16_f32 v101, v102, v103
	v_cvt_pk_bf16_f32 v102, v96, v97
	v_cvt_pk_bf16_f32 v103, v98, v99
	global_store_dwordx4 v[232:233], v[100:103], off offset:256
	v_mfma_f32_16x16x32_bf16 v[12:15], v[156:159], v[240:243], v[12:15]
	v_lshl_add_u64 v[232:233], v[232:233], 0, s[98:99]
	v_mul_f32_e32 v92, v236, v92
	v_mul_f32_e32 v93, v236, v93
	v_mul_f32_e32 v94, v236, v94
	v_mul_f32_e32 v95, v236, v95
	v_mfma_f32_16x16x32_bf16 v[8:11], v[164:167], v[240:243], v[8:11]
	v_mul_f32_e32 v88, v236, v88
	v_mul_f32_e32 v89, v236, v89
	v_mul_f32_e32 v90, v236, v90
	v_mul_f32_e32 v91, v236, v91
	v_cvt_pk_bf16_f32 v92, v92, v93
	s_setprio 0
	s_setprio 1
	v_mfma_f32_16x16x32_bf16 v[52:55], v[176:179], v[192:195], v[52:55]
	v_cvt_pk_bf16_f32 v93, v94, v95
	v_cvt_pk_bf16_f32 v94, v88, v89
	v_cvt_pk_bf16_f32 v95, v90, v91
	global_store_dwordx4 v[232:233], v[92:95], off
	v_mul_f32_e32 v84, v236, v84
	v_mfma_f32_16x16x32_bf16 v[48:51], v[184:187], v[192:195], v[48:51]
	v_mul_f32_e32 v85, v236, v85
	v_mul_f32_e32 v86, v236, v86
	v_mul_f32_e32 v87, v236, v87
	v_mul_f32_e32 v80, v236, v80
	v_mul_f32_e32 v81, v236, v81
	v_mfma_f32_16x16x32_bf16 v[36:39], v[176:179], v[200:203], v[36:39]
	v_mul_f32_e32 v82, v236, v82
	v_mul_f32_e32 v83, v236, v83
	v_cvt_pk_bf16_f32 v84, v84, v85
	v_cvt_pk_bf16_f32 v85, v86, v87
	v_cvt_pk_bf16_f32 v86, v80, v81
	v_mfma_f32_16x16x32_bf16 v[32:35], v[184:187], v[200:203], v[32:35]
	v_cvt_pk_bf16_f32 v87, v82, v83
	global_store_dwordx4 v[232:233], v[84:87], off offset:256
	v_lshl_add_u64 v[232:233], v[232:233], 0, s[98:99]
	v_mul_f32_e32 v76, v237, v76
	v_mul_f32_e32 v77, v237, v77
	v_mfma_f32_16x16x32_bf16 v[20:23], v[176:179], v[208:211], v[20:23]
	v_mul_f32_e32 v78, v237, v78
	v_mul_f32_e32 v79, v237, v79
	v_mul_f32_e32 v72, v237, v72
	v_mul_f32_e32 v73, v237, v73
	v_mul_f32_e32 v74, v237, v74
	v_mfma_f32_16x16x32_bf16 v[16:19], v[184:187], v[208:211], v[16:19]
	v_mul_f32_e32 v75, v237, v75
	v_cvt_pk_bf16_f32 v76, v76, v77
	v_cvt_pk_bf16_f32 v77, v78, v79
	v_cvt_pk_bf16_f32 v78, v72, v73
	v_cvt_pk_bf16_f32 v79, v74, v75
	v_mfma_f32_16x16x32_bf16 v[4:7], v[176:179], v[216:219], v[4:7]
	global_store_dwordx4 v[232:233], v[76:79], off
	v_mul_f32_e32 v68, v237, v68
	v_mul_f32_e32 v69, v237, v69
	v_mul_f32_e32 v70, v237, v70
	v_mul_f32_e32 v71, v237, v71
	v_mfma_f32_16x16x32_bf16 v[0:3], v[184:187], v[216:219], v[0:3]
	v_mul_f32_e32 v64, v237, v64
	v_mul_f32_e32 v65, v237, v65
	v_mul_f32_e32 v66, v237, v66
	v_mul_f32_e32 v67, v237, v67
	v_cvt_pk_bf16_f32 v68, v68, v69
	v_mfma_f32_16x16x32_bf16 v[52:55], v[180:183], v[196:199], v[52:55]
	v_cvt_pk_bf16_f32 v69, v70, v71
	v_cvt_pk_bf16_f32 v70, v64, v65
	v_cvt_pk_bf16_f32 v71, v66, v67
	global_store_dwordx4 v[232:233], v[68:71], off offset:256
	v_lshl_add_u64 v[232:233], v[232:233], 0, s[98:99]
	v_mfma_f32_16x16x32_bf16 v[48:51], v[188:191], v[196:199], v[48:51]
	v_lshl_add_u64 v[232:233], v[232:233], 0, s[98:99]
	v_lshl_add_u64 v[232:233], v[232:233], 0, s[98:99]
	v_lshl_add_u64 v[232:233], v[232:233], 0, s[98:99]
	v_lshl_add_u64 v[232:233], v[232:233], 0, s[98:99]
	v_mfma_f32_16x16x32_bf16 v[36:39], v[180:183], v[204:207], v[36:39]
	v_mfma_f32_16x16x32_bf16 v[32:35], v[188:191], v[204:207], v[32:35]
	v_mfma_f32_16x16x32_bf16 v[20:23], v[180:183], v[212:215], v[20:23]
	v_mfma_f32_16x16x32_bf16 v[16:19], v[188:191], v[212:215], v[16:19]
	v_mfma_f32_16x16x32_bf16 v[4:7], v[180:183], v[240:243], v[4:7]
	v_mfma_f32_16x16x32_bf16 v[0:3], v[188:191], v[240:243], v[0:3]
	s_setprio 0
	s_barrier
	v_lshl_add_u64 v[142:143], v[142:143], 0, s[80:81]
	v_lshl_add_u64 v[144:145], v[144:145], 0, s[80:81]

; __device__ __forceinline__ unsigned cvt_pk_bf16(float lo, float hi) { unsigned r; asm volatile("v_cvt_pk_bf16_f32 %0, %1, %2" : "=v"(r) : "v"(lo), "v"(hi)); return r; }
; __device__ __forceinline__ float gelu_tanh(float x) { const float u = 0.7978845608028654f * (x + 0.044715f * x * x * x); return x * fast_rcp(1.0f + fast_exp2(-2.0f * LOG2E * u)); }
;     __device__ __forceinline__ void operator()(const f32x4 (&acc)[2][2][4][2], const Unit& u, int wr, int wc, int fr, int fq) const {
;     ...
;             for (int m = 0; m < 4; ++m) { const int row = row0 + ai * HALF + m * 16; bf16_t* rowp = O + (size_t)row * ldc + col0; const float rs = rsv[ai][m];
; #pragma unroll
;                 for (int bj = 0; bj < 2; ++bj) { f32x4 v0 = acc[ai][bj][m][0] * rs, v1 = acc[ai][bj][m][1] * rs;
;                     if (ACT == 1) {
; #pragma unroll
;                         for (int j = 0; j < 4; ++j) { v0[j] = gelu_tanh(v0[j]); v1[j] = gelu_tanh(v1[j]); } }
;                     u32x4 w; w.x = cvt_pk_bf16(v0[0], v0[1]); w.y = cvt_pk_bf16(v0[2], v0[3]); w.z = cvt_pk_bf16(v1[0], v1[1]); w.w = cvt_pk_bf16(v1[2], v1[3]);
;                     *(u32x4*)(rowp + bj * HALF) = w; } }
.LBB0_357:
	s_nop 15
	s_nop 15
	s_lshl_b32 s98, s28, 5
	s_mov_b32 s99, 0
	v_pk_mul_f32 v[60:61], v[60:61], v[238:239] op_sel_hi:[1,0]
	v_pk_mul_f32 v[62:63], v[62:63], v[238:239] op_sel_hi:[1,0]
	v_pk_mul_f32 v[56:57], v[56:57], v[238:239] op_sel_hi:[1,0]
	v_pk_mul_f32 v[58:59], v[58:59], v[238:239] op_sel_hi:[1,0]
	v_cvt_pk_bf16_f32 v60, v60, v61
	v_cvt_pk_bf16_f32 v61, v62, v63
	v_cvt_pk_bf16_f32 v62, v56, v57
	v_cvt_pk_bf16_f32 v63, v58, v59
	global_store_dwordx4 v[232:233], v[60:63], off
	v_pk_mul_f32 v[52:53], v[52:53], v[238:239] op_sel_hi:[1,0]
	v_pk_mul_f32 v[54:55], v[54:55], v[238:239] op_sel_hi:[1,0]
	v_pk_mul_f32 v[48:49], v[48:49], v[238:239] op_sel_hi:[1,0]
	v_pk_mul_f32 v[50:51], v[50:51], v[238:239] op_sel_hi:[1,0]
	v_cvt_pk_bf16_f32 v52, v52, v53
	v_cvt_pk_bf16_f32 v53, v54, v55
	v_cvt_pk_bf16_f32 v54, v48, v49
	v_cvt_pk_bf16_f32 v55, v50, v51
	global_store_dwordx4 v[232:233], v[52:55], off offset:256
	v_lshl_add_u64 v[232:233], v[232:233], 0, s[98:99]
	v_pk_mul_f32 v[44:45], v[44:45], v[238:239] op_sel:[0,1]
	v_pk_mul_f32 v[46:47], v[46:47], v[238:239] op_sel:[0,1]
	v_pk_mul_f32 v[40:41], v[40:41], v[238:239] op_sel:[0,1]
	v_pk_mul_f32 v[42:43], v[42:43], v[238:239] op_sel:[0,1]
	v_cvt_pk_bf16_f32 v44, v44, v45
	v_cvt_pk_bf16_f32 v45, v46, v47
	v_cvt_pk_bf16_f32 v46, v40, v41
	v_cvt_pk_bf16_f32 v47, v42, v43
	global_store_dwordx4 v[232:233], v[44:47], off
	v_pk_mul_f32 v[36:37], v[36:37], v[238:239] op_sel:[0,1]
	v_pk_mul_f32 v[38:39], v[38:39], v[238:239] op_sel:[0,1]
	v_pk_mul_f32 v[32:33], v[32:33], v[238:239] op_sel:[0,1]
	v_pk_mul_f32 v[34:35], v[34:35], v[238:239] op_sel:[0,1]
	v_cvt_pk_bf16_f32 v36, v36, v37
	v_cvt_pk_bf16_f32 v37, v38, v39
	v_cvt_pk_bf16_f32 v38, v32, v33
	v_cvt_pk_bf16_f32 v39, v34, v35
	global_store_dwordx4 v[232:233], v[36:39], off offset:256
	v_lshl_add_u64 v[232:233], v[232:233], 0, s[98:99]
	v_pk_mul_f32 v[28:29], v[28:29], v[230:231] op_sel_hi:[1,0]
	v_pk_mul_f32 v[30:31], v[30:31], v[230:231] op_sel_hi:[1,0]
	v_pk_mul_f32 v[24:25], v[24:25], v[230:231] op_sel_hi:[1,0]
	v_pk_mul_f32 v[26:27], v[26:27], v[230:231] op_sel_hi:[1,0]
	v_cvt_pk_bf16_f32 v28, v28, v29
	v_cvt_pk_bf16_f32 v29, v30, v31
	v_cvt_pk_bf16_f32 v30, v24, v25
	v_cvt_pk_bf16_f32 v31, v26, v27
	global_store_dwordx4 v[232:233], v[28:31], off
	v_pk_mul_f32 v[20:21], v[20:21], v[230:231] op_sel_hi:[1,0]
	v_pk_mul_f32 v[22:23], v[22:23], v[230:231] op_sel_hi:[1,0]
	v_pk_mul_f32 v[16:17], v[16:17], v[230:231] op_sel_hi:[1,0]
	v_pk_mul_f32 v[18:19], v[18:19], v[230:231] op_sel_hi:[1,0]
	v_cvt_pk_bf16_f32 v20, v20, v21
	v_cvt_pk_bf16_f32 v21, v22, v23
	v_cvt_pk_bf16_f32 v22, v16, v17
	v_cvt_pk_bf16_f32 v23, v18, v19
	global_store_dwordx4 v[232:233], v[20:23], off offset:256
	v_lshl_add_u64 v[232:233], v[232:233], 0, s[98:99]
	v_pk_mul_f32 v[12:13], v[12:13], v[230:231] op_sel:[0,1]
	v_pk_mul_f32 v[14:15], v[14:15], v[230:231] op_sel:[0,1]
	v_pk_mul_f32 v[8:9], v[8:9], v[230:231] op_sel:[0,1]
	v_pk_mul_f32 v[10:11], v[10:11], v[230:231] op_sel:[0,1]
	v_cvt_pk_bf16_f32 v12, v12, v13
	v_cvt_pk_bf16_f32 v13, v14, v15
	v_cvt_pk_bf16_f32 v14, v8, v9
	v_cvt_pk_bf16_f32 v15, v10, v11
	global_store_dwordx4 v[232:233], v[12:15], off
	v_pk_mul_f32 v[4:5], v[4:5], v[230:231] op_sel:[0,1]
	v_pk_mul_f32 v[6:7], v[6:7], v[230:231] op_sel:[0,1]
	v_pk_mul_f32 v[0:1], v[0:1], v[230:231] op_sel:[0,1]
	v_pk_mul_f32 v[2:3], v[2:3], v[230:231] op_sel:[0,1]
	v_cvt_pk_bf16_f32 v4, v4, v5
	v_cvt_pk_bf16_f32 v5, v6, v7
	v_cvt_pk_bf16_f32 v6, v0, v1
	v_cvt_pk_bf16_f32 v7, v2, v3
	global_store_dwordx4 v[232:233], v[4:7], off offset:256
	s_mov_b32 s101, 0
	s_mov_b64 s[10:11], -1
	s_and_b64 vcc, exec, s[8:9]
	s_cbranch_vccnz .LBB0_345
	s_andn2_b64 vcc, exec, s[40:41]
	s_cbranch_vccnz .LBB0_344
	s_barrier
	s_branch .LBB0_344
.LBB0_360:
	v_mbcnt_lo_u32_b32 v225, -1, 0
	v_mbcnt_hi_u32_b32 v225, -1, v225
	v_mov_b32_e32 v224, 0x260
	v_and_b32_e32 v228, 64, v225
	v_add_u32_e32 v228, 64, v228
	v_xor_b32_e32 v229, 1, v225
	v_xor_b32_e32 v230, 2, v225
	v_xor_b32_e32 v231, 4, v225
	v_xor_b32_e32 v232, 8, v225
	v_xor_b32_e32 v233, 16, v225
	v_xor_b32_e32 v234, 32, v225
	v_mov_b32_e32 v236, 0xf149f2ca
	v_mov_b32_e32 v238, 0xfffff
	v_readlane_b32 s98, v255, 32
	v_lshl_add_u32 v172, s98, 9, v170
	s_waitcnt vmcnt(0)
	v_readlane_b32 s60, v255, 51
	s_mov_b32 s52, 0x30000
	s_movk_i32 s53, 0x2400
	s_mov_b32 s54, 0xf149f2ca
	s_mov_b64 s[56:57], 0x100000
	s_mov_b64 s[58:59], 0xfffff
	v_readlane_b32 s61, v255, 52
	s_barrier
